# removed per-phase s_setprio flips in the GEMM main loops
# speedup vs baseline: 1.0413x; 1.0100x over previous
.LBB0_645:
	s_add_u32 s44, s46, 0x100
	s_addc_u32 s45, s47, 0
	s_add_i32 s87, 0, 0x10000
	v_add_u32_e32 v118, s87, v191
	ds_read_b128 v[102:105], v118
	ds_read_b128 v[106:109], v118 offset:1024
	ds_read_b128 v[114:117], v118 offset:2048
	ds_read_b128 v[118:121], v118 offset:3072
	s_cmp_eq_u32 s86, 40
	s_cselect_b32 s53, s17, s45
	s_cselect_b32 s52, s16, s44
	s_cselect_b32 s49, s43, s85
	s_cselect_b32 s48, s42, s84
	v_lshl_add_u64 v[184:185], s[46:47], 0, v[178:179]
	s_add_i32 m0, s67, 0xc000
	ds_read_b128 v[122:125], v193
	ds_read_b128 v[126:129], v193 offset:1024
	ds_read_b128 v[134:137], v193 offset:2048
	ds_read_b128 v[138:141], v193 offset:3072
	ds_read_b128 v[162:165], v193 offset:4096
	ds_read_b128 v[166:169], v193 offset:5120
	ds_read_b128 v[170:173], v193 offset:6144
	ds_read_b128 v[180:183], v193 offset:7168
	global_load_lds_dwordx4 v[184:185], off
	v_lshl_add_u64 v[184:185], s[46:47], 0, v[176:177]
	s_add_i32 m0, s67, 0xe000
	s_nop 0
	global_load_lds_dwordx4 v[184:185], off
	s_waitcnt lgkmcnt(8)
	s_barrier
	s_waitcnt lgkmcnt(0)
	s_waitcnt lgkmcnt(0)
	v_mfma_f32_16x16x32_bf16 v[158:161], v[102:105], v[122:125], v[158:161]
	v_mfma_f32_16x16x32_bf16 v[154:157], v[114:117], v[122:125], v[154:157]
	v_mfma_f32_16x16x32_bf16 v[142:145], v[102:105], v[134:137], v[142:145]
	v_mfma_f32_16x16x32_bf16 v[130:133], v[114:117], v[134:137], v[130:133]
	v_mfma_f32_16x16x32_bf16 v[94:97], v[102:105], v[162:165], v[94:97]
	v_mfma_f32_16x16x32_bf16 v[90:93], v[114:117], v[162:165], v[90:93]
	v_mfma_f32_16x16x32_bf16 v[82:85], v[102:105], v[170:173], v[82:85]
	v_mfma_f32_16x16x32_bf16 v[74:77], v[114:117], v[170:173], v[74:77]
	v_mfma_f32_16x16x32_bf16 v[158:161], v[106:109], v[126:129], v[158:161]
	v_mfma_f32_16x16x32_bf16 v[154:157], v[118:121], v[126:129], v[154:157]
	v_mfma_f32_16x16x32_bf16 v[142:145], v[106:109], v[138:141], v[142:145]
	v_mfma_f32_16x16x32_bf16 v[130:133], v[118:121], v[138:141], v[130:133]
	v_mfma_f32_16x16x32_bf16 v[94:97], v[106:109], v[166:169], v[94:97]
	v_mfma_f32_16x16x32_bf16 v[90:93], v[118:121], v[166:169], v[90:93]
	v_mfma_f32_16x16x32_bf16 v[82:85], v[106:109], v[180:183], v[82:85]
	v_mfma_f32_16x16x32_bf16 v[74:77], v[118:121], v[180:183], v[74:77]
	s_barrier
	s_add_i32 s88, 0, 0x14000
	v_add_u32_e32 v188, s88, v191
	s_add_i32 s46, s87, s66
	ds_read_b128 v[184:187], v188
	ds_read_b128 v[196:199], v188 offset:1024
	ds_read_b128 v[204:207], v188 offset:2048
	ds_read_b128 v[208:211], v188 offset:3072
	v_lshl_add_u64 v[188:189], s[48:49], 0, v[0:1]
	s_mov_b32 m0, s46
	v_lshl_add_u64 v[200:201], s[48:49], 0, v[174:175]
	global_load_lds_dwordx4 v[188:189], off
	s_add_i32 m0, s46, 0x2000
	s_nop 0
	global_load_lds_dwordx4 v[200:201], off
	s_barrier
	s_waitcnt lgkmcnt(0)
	s_waitcnt lgkmcnt(0)
	v_mfma_f32_16x16x32_bf16 v[150:153], v[184:187], v[122:125], v[150:153]
	v_mfma_f32_16x16x32_bf16 v[110:113], v[184:187], v[134:137], v[110:113]
	v_mfma_f32_16x16x32_bf16 v[98:101], v[204:207], v[134:137], v[98:101]
	v_mfma_f32_16x16x32_bf16 v[86:89], v[184:187], v[162:165], v[86:89]
	v_mfma_f32_16x16x32_bf16 v[78:81], v[204:207], v[162:165], v[78:81]
	v_mfma_f32_16x16x32_bf16 v[70:73], v[184:187], v[170:173], v[70:73]
	v_mfma_f32_16x16x32_bf16 v[66:69], v[204:207], v[170:173], v[66:69]
	v_mfma_f32_16x16x32_bf16 v[150:153], v[196:199], v[126:129], v[150:153]
	v_mfma_f32_16x16x32_bf16 v[122:125], v[204:207], v[122:125], v[146:149]
	v_mfma_f32_16x16x32_bf16 v[110:113], v[196:199], v[138:141], v[110:113]
	v_mfma_f32_16x16x32_bf16 v[98:101], v[208:211], v[138:141], v[98:101]
	v_mfma_f32_16x16x32_bf16 v[86:89], v[196:199], v[166:169], v[86:89]
	v_mfma_f32_16x16x32_bf16 v[78:81], v[208:211], v[166:169], v[78:81]
	v_mfma_f32_16x16x32_bf16 v[70:73], v[196:199], v[180:183], v[70:73]
	v_mfma_f32_16x16x32_bf16 v[66:69], v[208:211], v[180:183], v[66:69]
	v_mfma_f32_16x16x32_bf16 v[122:125], v[208:211], v[126:129], v[122:125]
	s_mov_b32 m0, s67
	v_lshl_add_u64 v[202:203], s[52:53], 0, v[0:1]
	s_barrier
	ds_read_b128 v[126:129], v193 offset:16384
	ds_read_b128 v[134:137], v193 offset:17408
	ds_read_b128 v[138:141], v193 offset:18432
	ds_read_b128 v[146:149], v193 offset:19456
	ds_read_b128 v[162:165], v193 offset:20480
	ds_read_b128 v[166:169], v193 offset:21504
	ds_read_b128 v[170:173], v193 offset:22528
	ds_read_b128 v[180:183], v193 offset:23552
	global_load_lds_dwordx4 v[202:203], off
	v_lshl_add_u64 v[216:217], s[52:53], 0, v[174:175]
	s_mov_b32 m0, s68
	s_nop 0
	global_load_lds_dwordx4 v[216:217], off
	s_barrier
	s_waitcnt lgkmcnt(0)
	s_waitcnt lgkmcnt(0)
	v_mfma_f32_16x16x32_bf16 v[62:65], v[102:105], v[126:129], v[62:65]
	v_mfma_f32_16x16x32_bf16 v[58:61], v[114:117], v[126:129], v[58:61]
	v_mfma_f32_16x16x32_bf16 v[50:53], v[102:105], v[138:141], v[50:53]
	v_mfma_f32_16x16x32_bf16 v[42:45], v[114:117], v[138:141], v[42:45]
	v_mfma_f32_16x16x32_bf16 v[30:33], v[102:105], v[162:165], v[30:33]
	v_mfma_f32_16x16x32_bf16 v[26:29], v[114:117], v[162:165], v[26:29]
	v_mfma_f32_16x16x32_bf16 v[18:21], v[102:105], v[170:173], v[18:21]
	v_mfma_f32_16x16x32_bf16 v[10:13], v[114:117], v[170:173], v[10:13]
	v_mfma_f32_16x16x32_bf16 v[62:65], v[106:109], v[134:137], v[62:65]
	v_mfma_f32_16x16x32_bf16 v[58:61], v[118:121], v[134:137], v[58:61]
	v_mfma_f32_16x16x32_bf16 v[50:53], v[106:109], v[146:149], v[50:53]
	v_mfma_f32_16x16x32_bf16 v[42:45], v[118:121], v[146:149], v[42:45]
	v_mfma_f32_16x16x32_bf16 v[30:33], v[106:109], v[166:169], v[30:33]
	v_mfma_f32_16x16x32_bf16 v[26:29], v[118:121], v[166:169], v[26:29]
	v_mfma_f32_16x16x32_bf16 v[18:21], v[106:109], v[180:183], v[18:21]
	v_mfma_f32_16x16x32_bf16 v[10:13], v[118:121], v[180:183], v[10:13]
	s_barrier
	s_add_u32 s46, s48, 0xb0000
	s_addc_u32 s47, s49, 0
	s_add_i32 s87, s88, s66
	v_lshl_add_u64 v[102:103], s[46:47], 0, v[0:1]
	s_mov_b32 m0, s87
	s_nop 0
	global_load_lds_dwordx4 v[102:103], off
	v_lshl_add_u64 v[102:103], s[46:47], 0, v[174:175]
	s_add_i32 m0, s87, 0x2000
	s_nop 0
	global_load_lds_dwordx4 v[102:103], off
	s_waitcnt vmcnt(6)
	s_barrier
	v_mfma_f32_16x16x32_bf16 v[54:57], v[184:187], v[126:129], v[54:57]
	v_mfma_f32_16x16x32_bf16 v[46:49], v[204:207], v[126:129], v[46:49]
	v_mfma_f32_16x16x32_bf16 v[38:41], v[184:187], v[138:141], v[38:41]
	v_mfma_f32_16x16x32_bf16 v[34:37], v[204:207], v[138:141], v[34:37]
	v_mfma_f32_16x16x32_bf16 v[22:25], v[184:187], v[162:165], v[22:25]
	v_mfma_f32_16x16x32_bf16 v[14:17], v[204:207], v[162:165], v[14:17]
	v_mfma_f32_16x16x32_bf16 v[6:9], v[184:187], v[170:173], v[6:9]
	v_mfma_f32_16x16x32_bf16 v[2:5], v[204:207], v[170:173], v[2:5]
	v_mfma_f32_16x16x32_bf16 v[54:57], v[196:199], v[134:137], v[54:57]
	v_mfma_f32_16x16x32_bf16 v[46:49], v[208:211], v[134:137], v[46:49]
	v_mfma_f32_16x16x32_bf16 v[38:41], v[196:199], v[146:149], v[38:41]
	v_mfma_f32_16x16x32_bf16 v[34:37], v[208:211], v[146:149], v[34:37]
	v_mfma_f32_16x16x32_bf16 v[22:25], v[196:199], v[166:169], v[22:25]
	v_mfma_f32_16x16x32_bf16 v[14:17], v[208:211], v[166:169], v[14:17]
	v_mfma_f32_16x16x32_bf16 v[6:9], v[196:199], v[180:183], v[6:9]
	v_mfma_f32_16x16x32_bf16 v[2:5], v[208:211], v[180:183], v[2:5]
	s_add_i32 s87, 0, 0x18000
	v_add_u32_e32 v118, s87, v191
	s_barrier
	ds_read_b128 v[102:105], v118
	ds_read_b128 v[106:109], v118 offset:1024
	ds_read_b128 v[114:117], v118 offset:2048
	ds_read_b128 v[118:121], v118 offset:3072
	s_add_u32 s46, s52, 0xb0000
	s_addc_u32 s47, s53, 0
	s_mov_b32 m0, s69
	v_lshl_add_u64 v[146:147], s[46:47], 0, v[0:1]
	ds_read_b128 v[126:129], v193 offset:32768
	ds_read_b128 v[134:137], v193 offset:33792
	ds_read_b128 v[138:141], v193 offset:34816
	ds_read_b128 v[162:165], v193 offset:35840
	ds_read_b128 v[166:169], v193 offset:36864
	ds_read_b128 v[170:173], v193 offset:37888
	ds_read_b128 v[180:183], v193 offset:38912
	ds_read_b128 v[184:187], v193 offset:39936
	global_load_lds_dwordx4 v[146:147], off
	v_lshl_add_u64 v[146:147], s[46:47], 0, v[174:175]
	s_mov_b32 m0, s70
	s_nop 0
	global_load_lds_dwordx4 v[146:147], off
	s_waitcnt lgkmcnt(8)
	s_barrier
	s_waitcnt lgkmcnt(0)
	s_waitcnt lgkmcnt(0)
	v_mfma_f32_16x16x32_bf16 v[146:149], v[102:105], v[126:129], v[158:161]
	v_mfma_f32_16x16x32_bf16 v[158:161], v[106:109], v[134:137], v[146:149]
	v_mfma_f32_16x16x32_bf16 v[146:149], v[114:117], v[126:129], v[154:157]
	v_mfma_f32_16x16x32_bf16 v[142:145], v[102:105], v[138:141], v[142:145]
	v_mfma_f32_16x16x32_bf16 v[130:133], v[114:117], v[138:141], v[130:133]
	v_mfma_f32_16x16x32_bf16 v[94:97], v[102:105], v[166:169], v[94:97]
	v_mfma_f32_16x16x32_bf16 v[90:93], v[114:117], v[166:169], v[90:93]
	v_mfma_f32_16x16x32_bf16 v[82:85], v[102:105], v[180:183], v[82:85]
	v_mfma_f32_16x16x32_bf16 v[74:77], v[114:117], v[180:183], v[74:77]
	v_mfma_f32_16x16x32_bf16 v[154:157], v[118:121], v[134:137], v[146:149]
	v_mfma_f32_16x16x32_bf16 v[142:145], v[106:109], v[162:165], v[142:145]
	v_mfma_f32_16x16x32_bf16 v[130:133], v[118:121], v[162:165], v[130:133]
	v_mfma_f32_16x16x32_bf16 v[94:97], v[106:109], v[170:173], v[94:97]
	v_mfma_f32_16x16x32_bf16 v[90:93], v[118:121], v[170:173], v[90:93]
	v_mfma_f32_16x16x32_bf16 v[82:85], v[106:109], v[184:187], v[82:85]
	v_mfma_f32_16x16x32_bf16 v[74:77], v[118:121], v[184:187], v[74:77]
	s_barrier
	s_add_i32 s52, 0, 0x1c000
	v_add_u32_e32 v146, s52, v191
	s_add_i32 s46, s87, s66
	ds_read_b128 v[196:199], v146
	ds_read_b128 v[204:207], v146 offset:1024
	ds_read_b128 v[208:211], v146 offset:2048
	ds_read_b128 v[212:215], v146 offset:3072
	v_lshl_add_u64 v[146:147], v[188:189], 0, s[12:13]
	s_mov_b32 m0, s46
	s_nop 0
	global_load_lds_dwordx4 v[146:147], off
	v_lshl_add_u64 v[146:147], v[200:201], 0, s[12:13]
	s_add_i32 m0, s46, 0x2000
	s_nop 0
	global_load_lds_dwordx4 v[146:147], off
	s_barrier
	s_waitcnt lgkmcnt(0)
	s_waitcnt lgkmcnt(0)
	v_mfma_f32_16x16x32_bf16 v[146:149], v[196:199], v[126:129], v[150:153]
	v_mfma_f32_16x16x32_bf16 v[122:125], v[208:211], v[126:129], v[122:125]
	v_mfma_f32_16x16x32_bf16 v[110:113], v[196:199], v[138:141], v[110:113]
	v_mfma_f32_16x16x32_bf16 v[98:101], v[208:211], v[138:141], v[98:101]
	v_mfma_f32_16x16x32_bf16 v[86:89], v[196:199], v[166:169], v[86:89]
	v_mfma_f32_16x16x32_bf16 v[78:81], v[208:211], v[166:169], v[78:81]
	v_mfma_f32_16x16x32_bf16 v[70:73], v[196:199], v[180:183], v[70:73]
	v_mfma_f32_16x16x32_bf16 v[66:69], v[208:211], v[180:183], v[66:69]
	v_mfma_f32_16x16x32_bf16 v[150:153], v[204:207], v[134:137], v[146:149]
	v_mfma_f32_16x16x32_bf16 v[146:149], v[212:215], v[134:137], v[122:125]
	v_mfma_f32_16x16x32_bf16 v[110:113], v[204:207], v[162:165], v[110:113]
	v_mfma_f32_16x16x32_bf16 v[98:101], v[212:215], v[162:165], v[98:101]
	v_mfma_f32_16x16x32_bf16 v[86:89], v[204:207], v[170:173], v[86:89]
	v_mfma_f32_16x16x32_bf16 v[78:81], v[212:215], v[170:173], v[78:81]
	v_mfma_f32_16x16x32_bf16 v[70:73], v[204:207], v[184:187], v[70:73]
	v_mfma_f32_16x16x32_bf16 v[66:69], v[212:215], v[184:187], v[66:69]
	s_mov_b32 m0, s10
	v_lshl_add_u64 v[184:185], v[202:203], 0, s[12:13]
	s_barrier
	ds_read_b128 v[122:125], v193 offset:49152
	ds_read_b128 v[126:129], v193 offset:50176
	ds_read_b128 v[134:137], v193 offset:51200
	ds_read_b128 v[138:141], v193 offset:52224
	ds_read_b128 v[162:165], v193 offset:53248
	ds_read_b128 v[166:169], v193 offset:54272
	ds_read_b128 v[170:173], v193 offset:55296
	ds_read_b128 v[180:183], v193 offset:56320
	global_load_lds_dwordx4 v[184:185], off
	v_lshl_add_u64 v[184:185], v[216:217], 0, s[12:13]
	s_mov_b32 m0, s71
	s_nop 0
	global_load_lds_dwordx4 v[184:185], off
	s_barrier
	s_waitcnt lgkmcnt(0)
	s_waitcnt lgkmcnt(0)
	v_mfma_f32_16x16x32_bf16 v[62:65], v[102:105], v[122:125], v[62:65]
	v_mfma_f32_16x16x32_bf16 v[58:61], v[114:117], v[122:125], v[58:61]
	v_mfma_f32_16x16x32_bf16 v[50:53], v[102:105], v[134:137], v[50:53]
	v_mfma_f32_16x16x32_bf16 v[42:45], v[114:117], v[134:137], v[42:45]
	v_mfma_f32_16x16x32_bf16 v[30:33], v[102:105], v[162:165], v[30:33]
	v_mfma_f32_16x16x32_bf16 v[26:29], v[114:117], v[162:165], v[26:29]
	v_mfma_f32_16x16x32_bf16 v[18:21], v[102:105], v[170:173], v[18:21]
	v_mfma_f32_16x16x32_bf16 v[10:13], v[114:117], v[170:173], v[10:13]
	v_mfma_f32_16x16x32_bf16 v[62:65], v[106:109], v[126:129], v[62:65]
	v_mfma_f32_16x16x32_bf16 v[58:61], v[118:121], v[126:129], v[58:61]
	v_mfma_f32_16x16x32_bf16 v[50:53], v[106:109], v[138:141], v[50:53]
	v_mfma_f32_16x16x32_bf16 v[42:45], v[118:121], v[138:141], v[42:45]
	v_mfma_f32_16x16x32_bf16 v[30:33], v[106:109], v[166:169], v[30:33]
	v_mfma_f32_16x16x32_bf16 v[26:29], v[118:121], v[166:169], v[26:29]
	v_mfma_f32_16x16x32_bf16 v[18:21], v[106:109], v[180:183], v[18:21]
	v_mfma_f32_16x16x32_bf16 v[10:13], v[118:121], v[180:183], v[10:13]
	s_barrier
	s_add_u32 s46, s48, 0xb0080
	s_addc_u32 s47, s49, 0
	s_add_i32 s48, s52, s66
	v_lshl_add_u64 v[102:103], s[46:47], 0, v[0:1]
	s_mov_b32 m0, s48
	s_nop 0
	global_load_lds_dwordx4 v[102:103], off
	v_lshl_add_u64 v[102:103], s[46:47], 0, v[174:175]
	s_add_i32 m0, s48, 0x2000
	s_nop 0
	global_load_lds_dwordx4 v[102:103], off
	s_waitcnt vmcnt(6)
	s_barrier
	v_mfma_f32_16x16x32_bf16 v[54:57], v[196:199], v[122:125], v[54:57]
	v_mfma_f32_16x16x32_bf16 v[46:49], v[208:211], v[122:125], v[46:49]
	v_mfma_f32_16x16x32_bf16 v[38:41], v[196:199], v[134:137], v[38:41]
	v_mfma_f32_16x16x32_bf16 v[34:37], v[208:211], v[134:137], v[34:37]
	v_mfma_f32_16x16x32_bf16 v[22:25], v[196:199], v[162:165], v[22:25]
	v_mfma_f32_16x16x32_bf16 v[14:17], v[208:211], v[162:165], v[14:17]
	v_mfma_f32_16x16x32_bf16 v[6:9], v[196:199], v[170:173], v[6:9]
	v_mfma_f32_16x16x32_bf16 v[2:5], v[208:211], v[170:173], v[2:5]
	v_mfma_f32_16x16x32_bf16 v[54:57], v[204:207], v[126:129], v[54:57]
	v_mfma_f32_16x16x32_bf16 v[46:49], v[212:215], v[126:129], v[46:49]
	v_mfma_f32_16x16x32_bf16 v[38:41], v[204:207], v[138:141], v[38:41]
	v_mfma_f32_16x16x32_bf16 v[34:37], v[212:215], v[138:141], v[34:37]
	v_mfma_f32_16x16x32_bf16 v[22:25], v[204:207], v[166:169], v[22:25]
	v_mfma_f32_16x16x32_bf16 v[14:17], v[212:215], v[166:169], v[14:17]
	v_mfma_f32_16x16x32_bf16 v[6:9], v[204:207], v[180:183], v[6:9]
	v_mfma_f32_16x16x32_bf16 v[2:5], v[212:215], v[180:183], v[2:5]
	s_add_i32 s86, s86, 2
	s_add_u32 s84, s84, 0x100
	s_addc_u32 s85, s85, 0
	s_cmp_gt_u32 s86, 41
	s_mov_b64 s[46:47], s[44:45]
	s_barrier
	s_cbranch_scc0 .LBB0_645
	v_lshl_or_b32 v102, s83, 8, v192
	v_ashrrev_i32_e32 v103, 31, v102
	v_lshl_add_u32 v184, s82, 8, v190
	v_lshlrev_b64 v[180:181], 2, v[102:103]
	v_ashrrev_i32_e32 v185, 31, v184
	v_lshl_add_u64 v[102:103], s[8:9], 0, v[180:181]
	v_lshl_add_u64 v[106:107], s[14:15], 0, v[180:181]
	v_lshl_add_u64 v[162:163], v[184:185], 3, s[4:5]
	global_load_dwordx4 v[134:137], v[102:103], off
	global_load_dwordx4 v[138:141], v[106:107], off
	global_load_dwordx4 v[122:125], v[102:103], off offset:64
	global_load_dwordx4 v[126:129], v[106:107], off offset:64
	global_load_dwordx4 v[114:117], v[102:103], off offset:512
	global_load_dwordx4 v[118:121], v[106:107], off offset:512
	s_nop 0
	global_load_dwordx4 v[102:105], v[102:103], off offset:576
	s_nop 0
	global_load_dwordx4 v[106:109], v[106:107], off offset:576
	v_lshl_add_u32 v194, v184, 12, v180
	v_lshlrev_b32_e32 v238, 3, v184
	v_readlane_b32 s84, v255, 48
	s_mov_b32 s83, s80
	s_mov_b32 s82, s81
	s_mov_b64 s[48:49], s[42:43]
	s_mov_b64 s[46:47], s[16:17]
	v_readlane_b32 s85, v255, 49
	v_readlane_b32 s86, v255, 50
	s_add_u32 vcc_lo, s56, 0x0
	s_addc_u32 vcc_hi, s57, 0
	global_load_dwordx2 v[188:189], v238, s[4:5] offset:0
	global_load_dwordx4 v[162:165], v194, vcc offset:0
	global_load_dwordx4 v[166:169], v194, vcc offset:64
	global_load_dwordx4 v[170:173], v194, vcc offset:512
	global_load_dwordx4 v[180:183], v194, vcc offset:576
	s_add_u32 vcc_lo, s56, 0x10000
	s_addc_u32 vcc_hi, s57, 0
	global_load_dwordx2 v[236:237], v238, s[4:5] offset:128
	global_load_dwordx4 v[184:187], v194, vcc offset:0
	global_load_dwordx4 v[196:199], v194, vcc offset:64
	global_load_dwordx4 v[200:203], v194, vcc offset:512
	global_load_dwordx4 v[204:207], v194, vcc offset:576
	s_add_u32 vcc_lo, s56, 0x20000
	s_addc_u32 vcc_hi, s57, 0
	global_load_dwordx2 v[252:253], v238, s[4:5] offset:256
	global_load_dwordx4 v[208:211], v194, vcc offset:0
	global_load_dwordx4 v[212:215], v194, vcc offset:64
	global_load_dwordx4 v[216:219], v194, vcc offset:512
	global_load_dwordx4 v[220:223], v194, vcc offset:576
	s_add_u32 vcc_lo, s56, 0x30000
	s_addc_u32 vcc_hi, s57, 0
	global_load_dwordx2 v[248:249], v238, s[4:5] offset:384
	global_load_dwordx4 v[224:227], v194, vcc offset:0
	global_load_dwordx4 v[228:231], v194, vcc offset:64
	global_load_dwordx4 v[232:235], v194, vcc offset:512
	global_load_dwordx4 v[244:247], v194, vcc offset:576
	s_waitcnt vmcnt(10)
	s_add_u32 vcc_lo, s56, 0x0
	s_addc_u32 vcc_hi, s57, 0
	v_sub_f32_e32 v163, v163, v188
	v_sub_f32_e32 v162, v162, v188
	v_sub_f32_e32 v165, v165, v188
	v_sub_f32_e32 v164, v164, v188
	v_pk_mul_f32 v[164:165], v[188:189], v[164:165] op_sel:[1,0]
	v_pk_mul_f32 v[162:163], v[188:189], v[162:163] op_sel:[1,0]
	v_pk_fma_f32 v[164:165], v[136:137], v[164:165], v[140:141]
	v_pk_fma_f32 v[162:163], v[134:135], v[162:163], v[138:139]
	v_pk_fma_f32 v[160:161], v[164:165], s[60:61], v[160:161] op_sel_hi:[1,0,1]
	v_pk_fma_f32 v[158:159], v[162:163], s[60:61], v[158:159] op_sel_hi:[1,0,1]
	global_store_dwordx4 v194, v[158:161], vcc offset:0
	v_sub_f32_e32 v167, v167, v188
	v_sub_f32_e32 v166, v166, v188
	v_sub_f32_e32 v169, v169, v188
	v_sub_f32_e32 v168, v168, v188
	v_pk_mul_f32 v[168:169], v[188:189], v[168:169] op_sel:[1,0]
	v_pk_mul_f32 v[166:167], v[188:189], v[166:167] op_sel:[1,0]
	v_pk_fma_f32 v[168:169], v[124:125], v[168:169], v[128:129]
	v_pk_fma_f32 v[166:167], v[122:123], v[166:167], v[126:127]
	v_pk_fma_f32 v[156:157], v[168:169], s[60:61], v[156:157] op_sel_hi:[1,0,1]
	v_pk_fma_f32 v[154:155], v[166:167], s[60:61], v[154:155] op_sel_hi:[1,0,1]
	global_store_dwordx4 v194, v[154:157], vcc offset:64
	v_sub_f32_e32 v171, v171, v188
	v_sub_f32_e32 v170, v170, v188
	v_sub_f32_e32 v173, v173, v188
	v_sub_f32_e32 v172, v172, v188
	v_pk_mul_f32 v[172:173], v[188:189], v[172:173] op_sel:[1,0]
	v_pk_mul_f32 v[170:171], v[188:189], v[170:171] op_sel:[1,0]
	v_pk_fma_f32 v[172:173], v[116:117], v[172:173], v[120:121]
	v_pk_fma_f32 v[170:171], v[114:115], v[170:171], v[118:119]
	v_pk_fma_f32 v[152:153], v[172:173], s[60:61], v[152:153] op_sel_hi:[1,0,1]
	v_pk_fma_f32 v[150:151], v[170:171], s[60:61], v[150:151] op_sel_hi:[1,0,1]
	global_store_dwordx4 v194, v[150:153], vcc offset:512
	v_sub_f32_e32 v181, v181, v188
	v_sub_f32_e32 v180, v180, v188
	v_sub_f32_e32 v183, v183, v188
	v_sub_f32_e32 v182, v182, v188
	v_pk_mul_f32 v[182:183], v[188:189], v[182:183] op_sel:[1,0]
	v_pk_mul_f32 v[180:181], v[188:189], v[180:181] op_sel:[1,0]
	v_pk_fma_f32 v[182:183], v[104:105], v[182:183], v[108:109]
	v_pk_fma_f32 v[180:181], v[102:103], v[180:181], v[106:107]
	v_pk_fma_f32 v[148:149], v[182:183], s[60:61], v[148:149] op_sel_hi:[1,0,1]
	v_pk_fma_f32 v[146:147], v[180:181], s[60:61], v[146:147] op_sel_hi:[1,0,1]
	global_store_dwordx4 v194, v[146:149], vcc offset:576
	s_add_u32 vcc_lo, s56, 0x10000
	s_addc_u32 vcc_hi, s57, 0
	v_sub_f32_e32 v185, v185, v236
	v_sub_f32_e32 v184, v184, v236
	v_sub_f32_e32 v187, v187, v236
	v_sub_f32_e32 v186, v186, v236
	v_pk_mul_f32 v[186:187], v[236:237], v[186:187] op_sel:[1,0]
	v_pk_mul_f32 v[184:185], v[236:237], v[184:185] op_sel:[1,0]
	v_pk_fma_f32 v[186:187], v[136:137], v[186:187], v[140:141]
	v_pk_fma_f32 v[184:185], v[134:135], v[184:185], v[138:139]
	v_pk_fma_f32 v[144:145], v[186:187], s[60:61], v[144:145] op_sel_hi:[1,0,1]
	v_pk_fma_f32 v[142:143], v[184:185], s[60:61], v[142:143] op_sel_hi:[1,0,1]
	global_store_dwordx4 v194, v[142:145], vcc offset:0
	v_sub_f32_e32 v197, v197, v236
	v_sub_f32_e32 v196, v196, v236
	v_sub_f32_e32 v199, v199, v236
	v_sub_f32_e32 v198, v198, v236
	v_pk_mul_f32 v[198:199], v[236:237], v[198:199] op_sel:[1,0]
	v_pk_mul_f32 v[196:197], v[236:237], v[196:197] op_sel:[1,0]
	v_pk_fma_f32 v[198:199], v[124:125], v[198:199], v[128:129]
	v_pk_fma_f32 v[196:197], v[122:123], v[196:197], v[126:127]
	v_pk_fma_f32 v[132:133], v[198:199], s[60:61], v[132:133] op_sel_hi:[1,0,1]
	v_pk_fma_f32 v[130:131], v[196:197], s[60:61], v[130:131] op_sel_hi:[1,0,1]
	global_store_dwordx4 v194, v[130:133], vcc offset:64
	v_sub_f32_e32 v201, v201, v236
	v_sub_f32_e32 v200, v200, v236
	v_sub_f32_e32 v203, v203, v236
	v_sub_f32_e32 v202, v202, v236
	v_pk_mul_f32 v[202:203], v[236:237], v[202:203] op_sel:[1,0]
	v_pk_mul_f32 v[200:201], v[236:237], v[200:201] op_sel:[1,0]
	v_pk_fma_f32 v[202:203], v[116:117], v[202:203], v[120:121]
	v_pk_fma_f32 v[200:201], v[114:115], v[200:201], v[118:119]
	v_pk_fma_f32 v[112:113], v[202:203], s[60:61], v[112:113] op_sel_hi:[1,0,1]
	v_pk_fma_f32 v[110:111], v[200:201], s[60:61], v[110:111] op_sel_hi:[1,0,1]
	global_store_dwordx4 v194, v[110:113], vcc offset:512
	v_sub_f32_e32 v205, v205, v236
	v_sub_f32_e32 v204, v204, v236
	v_sub_f32_e32 v207, v207, v236
	v_sub_f32_e32 v206, v206, v236
	v_pk_mul_f32 v[206:207], v[236:237], v[206:207] op_sel:[1,0]
	v_pk_mul_f32 v[204:205], v[236:237], v[204:205] op_sel:[1,0]
	v_pk_fma_f32 v[206:207], v[104:105], v[206:207], v[108:109]
	v_pk_fma_f32 v[204:205], v[102:103], v[204:205], v[106:107]
	v_pk_fma_f32 v[100:101], v[206:207], s[60:61], v[100:101] op_sel_hi:[1,0,1]
	v_pk_fma_f32 v[98:99], v[204:205], s[60:61], v[98:99] op_sel_hi:[1,0,1]
	global_store_dwordx4 v194, v[98:101], vcc offset:576
	s_add_u32 vcc_lo, s56, 0x80000
	s_addc_u32 vcc_hi, s57, 0
	global_load_dwordx2 v[188:189], v238, s[4:5] offset:1024
	global_load_dwordx4 v[158:161], v194, vcc offset:0
	global_load_dwordx4 v[154:157], v194, vcc offset:64
	global_load_dwordx4 v[150:153], v194, vcc offset:512
	global_load_dwordx4 v[146:149], v194, vcc offset:576
	s_add_u32 vcc_lo, s56, 0x90000
	s_addc_u32 vcc_hi, s57, 0
	global_load_dwordx2 v[236:237], v238, s[4:5] offset:1152
	global_load_dwordx4 v[142:145], v194, vcc offset:0
	global_load_dwordx4 v[130:133], v194, vcc offset:64
	global_load_dwordx4 v[110:113], v194, vcc offset:512
	global_load_dwordx4 v[98:101], v194, vcc offset:576
	s_waitcnt vmcnt(18)
	s_add_u32 vcc_lo, s56, 0x20000
	s_addc_u32 vcc_hi, s57, 0
	v_sub_f32_e32 v209, v209, v252
	v_sub_f32_e32 v208, v208, v252
	v_sub_f32_e32 v211, v211, v252
	v_sub_f32_e32 v210, v210, v252
	v_pk_mul_f32 v[210:211], v[252:253], v[210:211] op_sel:[1,0]
	v_pk_mul_f32 v[208:209], v[252:253], v[208:209] op_sel:[1,0]
	v_pk_fma_f32 v[210:211], v[136:137], v[210:211], v[140:141]
	v_pk_fma_f32 v[208:209], v[134:135], v[208:209], v[138:139]
	v_pk_fma_f32 v[96:97], v[210:211], s[60:61], v[96:97] op_sel_hi:[1,0,1]
	v_pk_fma_f32 v[94:95], v[208:209], s[60:61], v[94:95] op_sel_hi:[1,0,1]
	global_store_dwordx4 v194, v[94:97], vcc offset:0
	v_sub_f32_e32 v213, v213, v252
	v_sub_f32_e32 v212, v212, v252
	v_sub_f32_e32 v215, v215, v252
	v_sub_f32_e32 v214, v214, v252
	v_pk_mul_f32 v[214:215], v[252:253], v[214:215] op_sel:[1,0]
	v_pk_mul_f32 v[212:213], v[252:253], v[212:213] op_sel:[1,0]
	v_pk_fma_f32 v[214:215], v[124:125], v[214:215], v[128:129]
	v_pk_fma_f32 v[212:213], v[122:123], v[212:213], v[126:127]
	v_pk_fma_f32 v[92:93], v[214:215], s[60:61], v[92:93] op_sel_hi:[1,0,1]
	v_pk_fma_f32 v[90:91], v[212:213], s[60:61], v[90:91] op_sel_hi:[1,0,1]
	global_store_dwordx4 v194, v[90:93], vcc offset:64
	v_sub_f32_e32 v217, v217, v252
	v_sub_f32_e32 v216, v216, v252
	v_sub_f32_e32 v219, v219, v252
	v_sub_f32_e32 v218, v218, v252
	v_pk_mul_f32 v[218:219], v[252:253], v[218:219] op_sel:[1,0]
	v_pk_mul_f32 v[216:217], v[252:253], v[216:217] op_sel:[1,0]
	v_pk_fma_f32 v[218:219], v[116:117], v[218:219], v[120:121]
	v_pk_fma_f32 v[216:217], v[114:115], v[216:217], v[118:119]
	v_pk_fma_f32 v[88:89], v[218:219], s[60:61], v[88:89] op_sel_hi:[1,0,1]
	v_pk_fma_f32 v[86:87], v[216:217], s[60:61], v[86:87] op_sel_hi:[1,0,1]
	global_store_dwordx4 v194, v[86:89], vcc offset:512
	v_sub_f32_e32 v221, v221, v252
	v_sub_f32_e32 v220, v220, v252
	v_sub_f32_e32 v223, v223, v252
	v_sub_f32_e32 v222, v222, v252
	v_pk_mul_f32 v[222:223], v[252:253], v[222:223] op_sel:[1,0]
	v_pk_mul_f32 v[220:221], v[252:253], v[220:221] op_sel:[1,0]
	v_pk_fma_f32 v[222:223], v[104:105], v[222:223], v[108:109]
	v_pk_fma_f32 v[220:221], v[102:103], v[220:221], v[106:107]
	v_pk_fma_f32 v[80:81], v[222:223], s[60:61], v[80:81] op_sel_hi:[1,0,1]
	v_pk_fma_f32 v[78:79], v[220:221], s[60:61], v[78:79] op_sel_hi:[1,0,1]
	global_store_dwordx4 v194, v[78:81], vcc offset:576
	s_add_u32 vcc_lo, s56, 0x30000
	s_addc_u32 vcc_hi, s57, 0
	v_sub_f32_e32 v225, v225, v248
	v_sub_f32_e32 v224, v224, v248
	v_sub_f32_e32 v227, v227, v248
	v_sub_f32_e32 v226, v226, v248
	v_pk_mul_f32 v[226:227], v[248:249], v[226:227] op_sel:[1,0]
	v_pk_mul_f32 v[224:225], v[248:249], v[224:225] op_sel:[1,0]
	v_pk_fma_f32 v[226:227], v[136:137], v[226:227], v[140:141]
	v_pk_fma_f32 v[224:225], v[134:135], v[224:225], v[138:139]
	v_pk_fma_f32 v[84:85], v[226:227], s[60:61], v[84:85] op_sel_hi:[1,0,1]
	v_pk_fma_f32 v[82:83], v[224:225], s[60:61], v[82:83] op_sel_hi:[1,0,1]
	global_store_dwordx4 v194, v[82:85], vcc offset:0
	v_sub_f32_e32 v229, v229, v248
	v_sub_f32_e32 v228, v228, v248
	v_sub_f32_e32 v231, v231, v248
	v_sub_f32_e32 v230, v230, v248
	v_pk_mul_f32 v[230:231], v[248:249], v[230:231] op_sel:[1,0]
	v_pk_mul_f32 v[228:229], v[248:249], v[228:229] op_sel:[1,0]
	v_pk_fma_f32 v[230:231], v[124:125], v[230:231], v[128:129]
	v_pk_fma_f32 v[228:229], v[122:123], v[228:229], v[126:127]
	v_pk_fma_f32 v[76:77], v[230:231], s[60:61], v[76:77] op_sel_hi:[1,0,1]
	v_pk_fma_f32 v[74:75], v[228:229], s[60:61], v[74:75] op_sel_hi:[1,0,1]
	global_store_dwordx4 v194, v[74:77], vcc offset:64
	v_sub_f32_e32 v233, v233, v248
	v_sub_f32_e32 v232, v232, v248
	v_sub_f32_e32 v235, v235, v248
	v_sub_f32_e32 v234, v234, v248
	v_pk_mul_f32 v[234:235], v[248:249], v[234:235] op_sel:[1,0]
	v_pk_mul_f32 v[232:233], v[248:249], v[232:233] op_sel:[1,0]
	v_pk_fma_f32 v[234:235], v[116:117], v[234:235], v[120:121]
	v_pk_fma_f32 v[232:233], v[114:115], v[232:233], v[118:119]
	v_pk_fma_f32 v[72:73], v[234:235], s[60:61], v[72:73] op_sel_hi:[1,0,1]
	v_pk_fma_f32 v[70:71], v[232:233], s[60:61], v[70:71] op_sel_hi:[1,0,1]
	global_store_dwordx4 v194, v[70:73], vcc offset:512
	v_sub_f32_e32 v245, v245, v248
	v_sub_f32_e32 v244, v244, v248
	v_sub_f32_e32 v247, v247, v248
	v_sub_f32_e32 v246, v246, v248
	v_pk_mul_f32 v[246:247], v[248:249], v[246:247] op_sel:[1,0]
	v_pk_mul_f32 v[244:245], v[248:249], v[244:245] op_sel:[1,0]
	v_pk_fma_f32 v[246:247], v[104:105], v[246:247], v[108:109]
	v_pk_fma_f32 v[244:245], v[102:103], v[244:245], v[106:107]
	v_pk_fma_f32 v[68:69], v[246:247], s[60:61], v[68:69] op_sel_hi:[1,0,1]
	v_pk_fma_f32 v[66:67], v[244:245], s[60:61], v[66:67] op_sel_hi:[1,0,1]
	global_store_dwordx4 v194, v[66:69], vcc offset:576
	s_add_u32 vcc_lo, s56, 0xa0000
	s_addc_u32 vcc_hi, s57, 0
	global_load_dwordx2 v[252:253], v238, s[4:5] offset:1280
	global_load_dwordx4 v[94:97], v194, vcc offset:0
	global_load_dwordx4 v[90:93], v194, vcc offset:64
	global_load_dwordx4 v[86:89], v194, vcc offset:512
	global_load_dwordx4 v[78:81], v194, vcc offset:576
	s_add_u32 vcc_lo, s56, 0xb0000
	s_addc_u32 vcc_hi, s57, 0
	global_load_dwordx2 v[248:249], v238, s[4:5] offset:1408
	global_load_dwordx4 v[82:85], v194, vcc offset:0
	global_load_dwordx4 v[74:77], v194, vcc offset:64
	global_load_dwordx4 v[70:73], v194, vcc offset:512
	global_load_dwordx4 v[66:69], v194, vcc offset:576
	s_waitcnt vmcnt(18)
	s_add_u32 vcc_lo, s56, 0x80000
	s_addc_u32 vcc_hi, s57, 0
	v_sub_f32_e32 v159, v159, v188
	v_sub_f32_e32 v158, v158, v188
	v_sub_f32_e32 v161, v161, v188
	v_sub_f32_e32 v160, v160, v188
	v_pk_mul_f32 v[160:161], v[188:189], v[160:161] op_sel:[1,0]
	v_pk_mul_f32 v[158:159], v[188:189], v[158:159] op_sel:[1,0]
	v_pk_fma_f32 v[160:161], v[136:137], v[160:161], v[140:141]
	v_pk_fma_f32 v[158:159], v[134:135], v[158:159], v[138:139]
	v_pk_fma_f32 v[64:65], v[160:161], s[60:61], v[64:65] op_sel_hi:[1,0,1]
	v_pk_fma_f32 v[62:63], v[158:159], s[60:61], v[62:63] op_sel_hi:[1,0,1]
	global_store_dwordx4 v194, v[62:65], vcc offset:0
	v_sub_f32_e32 v155, v155, v188
	v_sub_f32_e32 v154, v154, v188
	v_sub_f32_e32 v157, v157, v188
	v_sub_f32_e32 v156, v156, v188
	v_pk_mul_f32 v[156:157], v[188:189], v[156:157] op_sel:[1,0]
	v_pk_mul_f32 v[154:155], v[188:189], v[154:155] op_sel:[1,0]
	v_pk_fma_f32 v[156:157], v[124:125], v[156:157], v[128:129]
	v_pk_fma_f32 v[154:155], v[122:123], v[154:155], v[126:127]
	v_pk_fma_f32 v[60:61], v[156:157], s[60:61], v[60:61] op_sel_hi:[1,0,1]
	v_pk_fma_f32 v[58:59], v[154:155], s[60:61], v[58:59] op_sel_hi:[1,0,1]
	global_store_dwordx4 v194, v[58:61], vcc offset:64
	v_sub_f32_e32 v151, v151, v188
	v_sub_f32_e32 v150, v150, v188
	v_sub_f32_e32 v153, v153, v188
	v_sub_f32_e32 v152, v152, v188
	v_pk_mul_f32 v[152:153], v[188:189], v[152:153] op_sel:[1,0]
	v_pk_mul_f32 v[150:151], v[188:189], v[150:151] op_sel:[1,0]
	v_pk_fma_f32 v[152:153], v[116:117], v[152:153], v[120:121]
	v_pk_fma_f32 v[150:151], v[114:115], v[150:151], v[118:119]
	v_pk_fma_f32 v[56:57], v[152:153], s[60:61], v[56:57] op_sel_hi:[1,0,1]
	v_pk_fma_f32 v[54:55], v[150:151], s[60:61], v[54:55] op_sel_hi:[1,0,1]
	global_store_dwordx4 v194, v[54:57], vcc offset:512
	v_sub_f32_e32 v147, v147, v188
	v_sub_f32_e32 v146, v146, v188
	v_sub_f32_e32 v149, v149, v188
	v_sub_f32_e32 v148, v148, v188
	v_pk_mul_f32 v[148:149], v[188:189], v[148:149] op_sel:[1,0]
	v_pk_mul_f32 v[146:147], v[188:189], v[146:147] op_sel:[1,0]
	v_pk_fma_f32 v[148:149], v[104:105], v[148:149], v[108:109]
	v_pk_fma_f32 v[146:147], v[102:103], v[146:147], v[106:107]
	v_pk_fma_f32 v[48:49], v[148:149], s[60:61], v[48:49] op_sel_hi:[1,0,1]
	v_pk_fma_f32 v[46:47], v[146:147], s[60:61], v[46:47] op_sel_hi:[1,0,1]
	global_store_dwordx4 v194, v[46:49], vcc offset:576
	s_add_u32 vcc_lo, s56, 0x90000
	s_addc_u32 vcc_hi, s57, 0
	v_sub_f32_e32 v143, v143, v236
	v_sub_f32_e32 v142, v142, v236
	v_sub_f32_e32 v145, v145, v236
	v_sub_f32_e32 v144, v144, v236
	v_pk_mul_f32 v[144:145], v[236:237], v[144:145] op_sel:[1,0]
	v_pk_mul_f32 v[142:143], v[236:237], v[142:143] op_sel:[1,0]
	v_pk_fma_f32 v[144:145], v[136:137], v[144:145], v[140:141]
	v_pk_fma_f32 v[142:143], v[134:135], v[142:143], v[138:139]
	v_pk_fma_f32 v[52:53], v[144:145], s[60:61], v[52:53] op_sel_hi:[1,0,1]
	v_pk_fma_f32 v[50:51], v[142:143], s[60:61], v[50:51] op_sel_hi:[1,0,1]
	global_store_dwordx4 v194, v[50:53], vcc offset:0
	v_sub_f32_e32 v131, v131, v236
	v_sub_f32_e32 v130, v130, v236
	v_sub_f32_e32 v133, v133, v236
	v_sub_f32_e32 v132, v132, v236
	v_pk_mul_f32 v[132:133], v[236:237], v[132:133] op_sel:[1,0]
	v_pk_mul_f32 v[130:131], v[236:237], v[130:131] op_sel:[1,0]
	v_pk_fma_f32 v[132:133], v[124:125], v[132:133], v[128:129]
	v_pk_fma_f32 v[130:131], v[122:123], v[130:131], v[126:127]
	v_pk_fma_f32 v[44:45], v[132:133], s[60:61], v[44:45] op_sel_hi:[1,0,1]
	v_pk_fma_f32 v[42:43], v[130:131], s[60:61], v[42:43] op_sel_hi:[1,0,1]
	global_store_dwordx4 v194, v[42:45], vcc offset:64
	v_sub_f32_e32 v111, v111, v236
	v_sub_f32_e32 v110, v110, v236
	v_sub_f32_e32 v113, v113, v236
	v_sub_f32_e32 v112, v112, v236
	v_pk_mul_f32 v[112:113], v[236:237], v[112:113] op_sel:[1,0]
	v_pk_mul_f32 v[110:111], v[236:237], v[110:111] op_sel:[1,0]
	v_pk_fma_f32 v[112:113], v[116:117], v[112:113], v[120:121]
	v_pk_fma_f32 v[110:111], v[114:115], v[110:111], v[118:119]
	v_pk_fma_f32 v[40:41], v[112:113], s[60:61], v[40:41] op_sel_hi:[1,0,1]
	v_pk_fma_f32 v[38:39], v[110:111], s[60:61], v[38:39] op_sel_hi:[1,0,1]
	global_store_dwordx4 v194, v[38:41], vcc offset:512
	v_sub_f32_e32 v99, v99, v236
	v_sub_f32_e32 v98, v98, v236
	v_sub_f32_e32 v101, v101, v236
	v_sub_f32_e32 v100, v100, v236
	v_pk_mul_f32 v[100:101], v[236:237], v[100:101] op_sel:[1,0]
	v_pk_mul_f32 v[98:99], v[236:237], v[98:99] op_sel:[1,0]
	v_pk_fma_f32 v[100:101], v[104:105], v[100:101], v[108:109]
	v_pk_fma_f32 v[98:99], v[102:103], v[98:99], v[106:107]
	v_pk_fma_f32 v[36:37], v[100:101], s[60:61], v[36:37] op_sel_hi:[1,0,1]
	v_pk_fma_f32 v[34:35], v[98:99], s[60:61], v[34:35] op_sel_hi:[1,0,1]
	global_store_dwordx4 v194, v[34:37], vcc offset:576
	s_waitcnt vmcnt(8)
	s_add_u32 vcc_lo, s56, 0xa0000
	s_addc_u32 vcc_hi, s57, 0
	v_sub_f32_e32 v95, v95, v252
	v_sub_f32_e32 v94, v94, v252
	v_sub_f32_e32 v97, v97, v252
	v_sub_f32_e32 v96, v96, v252
	v_pk_mul_f32 v[96:97], v[252:253], v[96:97] op_sel:[1,0]
	v_pk_mul_f32 v[94:95], v[252:253], v[94:95] op_sel:[1,0]
	v_pk_fma_f32 v[96:97], v[136:137], v[96:97], v[140:141]
	v_pk_fma_f32 v[94:95], v[134:135], v[94:95], v[138:139]
	v_pk_fma_f32 v[32:33], v[96:97], s[60:61], v[32:33] op_sel_hi:[1,0,1]
	v_pk_fma_f32 v[30:31], v[94:95], s[60:61], v[30:31] op_sel_hi:[1,0,1]
	global_store_dwordx4 v194, v[30:33], vcc offset:0
	v_sub_f32_e32 v91, v91, v252
	v_sub_f32_e32 v90, v90, v252
	v_sub_f32_e32 v93, v93, v252
	v_sub_f32_e32 v92, v92, v252
	v_pk_mul_f32 v[92:93], v[252:253], v[92:93] op_sel:[1,0]
	v_pk_mul_f32 v[90:91], v[252:253], v[90:91] op_sel:[1,0]
	v_pk_fma_f32 v[92:93], v[124:125], v[92:93], v[128:129]
	v_pk_fma_f32 v[90:91], v[122:123], v[90:91], v[126:127]
	v_pk_fma_f32 v[28:29], v[92:93], s[60:61], v[28:29] op_sel_hi:[1,0,1]
	v_pk_fma_f32 v[26:27], v[90:91], s[60:61], v[26:27] op_sel_hi:[1,0,1]
	global_store_dwordx4 v194, v[26:29], vcc offset:64
	v_sub_f32_e32 v87, v87, v252
	v_sub_f32_e32 v86, v86, v252
	v_sub_f32_e32 v89, v89, v252
	v_sub_f32_e32 v88, v88, v252
	v_pk_mul_f32 v[88:89], v[252:253], v[88:89] op_sel:[1,0]
	v_pk_mul_f32 v[86:87], v[252:253], v[86:87] op_sel:[1,0]
	v_pk_fma_f32 v[88:89], v[116:117], v[88:89], v[120:121]
	v_pk_fma_f32 v[86:87], v[114:115], v[86:87], v[118:119]
	v_pk_fma_f32 v[24:25], v[88:89], s[60:61], v[24:25] op_sel_hi:[1,0,1]
	v_pk_fma_f32 v[22:23], v[86:87], s[60:61], v[22:23] op_sel_hi:[1,0,1]
	global_store_dwordx4 v194, v[22:25], vcc offset:512
	v_sub_f32_e32 v79, v79, v252
	v_sub_f32_e32 v78, v78, v252
	v_sub_f32_e32 v81, v81, v252
	v_sub_f32_e32 v80, v80, v252
	v_pk_mul_f32 v[80:81], v[252:253], v[80:81] op_sel:[1,0]
	v_pk_mul_f32 v[78:79], v[252:253], v[78:79] op_sel:[1,0]
	v_pk_fma_f32 v[80:81], v[104:105], v[80:81], v[108:109]
	v_pk_fma_f32 v[78:79], v[102:103], v[78:79], v[106:107]
	v_pk_fma_f32 v[16:17], v[80:81], s[60:61], v[16:17] op_sel_hi:[1,0,1]
	v_pk_fma_f32 v[14:15], v[78:79], s[60:61], v[14:15] op_sel_hi:[1,0,1]
	global_store_dwordx4 v194, v[14:17], vcc offset:576
	s_add_u32 vcc_lo, s56, 0xb0000
	s_addc_u32 vcc_hi, s57, 0
	v_sub_f32_e32 v83, v83, v248
	v_sub_f32_e32 v82, v82, v248
	v_sub_f32_e32 v85, v85, v248
	v_sub_f32_e32 v84, v84, v248
	v_pk_mul_f32 v[84:85], v[248:249], v[84:85] op_sel:[1,0]
	v_pk_mul_f32 v[82:83], v[248:249], v[82:83] op_sel:[1,0]
	v_pk_fma_f32 v[84:85], v[136:137], v[84:85], v[140:141]
	v_pk_fma_f32 v[82:83], v[134:135], v[82:83], v[138:139]
	v_pk_fma_f32 v[20:21], v[84:85], s[60:61], v[20:21] op_sel_hi:[1,0,1]
	v_pk_fma_f32 v[18:19], v[82:83], s[60:61], v[18:19] op_sel_hi:[1,0,1]
	global_store_dwordx4 v194, v[18:21], vcc offset:0
	v_sub_f32_e32 v75, v75, v248
	v_sub_f32_e32 v74, v74, v248
	v_sub_f32_e32 v77, v77, v248
	v_sub_f32_e32 v76, v76, v248
	v_pk_mul_f32 v[76:77], v[248:249], v[76:77] op_sel:[1,0]
	v_pk_mul_f32 v[74:75], v[248:249], v[74:75] op_sel:[1,0]
	v_pk_fma_f32 v[76:77], v[124:125], v[76:77], v[128:129]
	v_pk_fma_f32 v[74:75], v[122:123], v[74:75], v[126:127]
	v_pk_fma_f32 v[12:13], v[76:77], s[60:61], v[12:13] op_sel_hi:[1,0,1]
	v_pk_fma_f32 v[10:11], v[74:75], s[60:61], v[10:11] op_sel_hi:[1,0,1]
	global_store_dwordx4 v194, v[10:13], vcc offset:64
	v_sub_f32_e32 v71, v71, v248
	v_sub_f32_e32 v70, v70, v248
	v_sub_f32_e32 v73, v73, v248
	v_sub_f32_e32 v72, v72, v248
	v_pk_mul_f32 v[72:73], v[248:249], v[72:73] op_sel:[1,0]
	v_pk_mul_f32 v[70:71], v[248:249], v[70:71] op_sel:[1,0]
	v_pk_fma_f32 v[72:73], v[116:117], v[72:73], v[120:121]
	v_pk_fma_f32 v[70:71], v[114:115], v[70:71], v[118:119]
	v_pk_fma_f32 v[8:9], v[72:73], s[60:61], v[8:9] op_sel_hi:[1,0,1]
	v_pk_fma_f32 v[6:7], v[70:71], s[60:61], v[6:7] op_sel_hi:[1,0,1]
	global_store_dwordx4 v194, v[6:9], vcc offset:512
	v_sub_f32_e32 v67, v67, v248
	v_sub_f32_e32 v66, v66, v248
	v_sub_f32_e32 v69, v69, v248
	v_sub_f32_e32 v68, v68, v248
	v_pk_mul_f32 v[68:69], v[248:249], v[68:69] op_sel:[1,0]
	v_pk_mul_f32 v[66:67], v[248:249], v[66:67] op_sel:[1,0]
	v_pk_fma_f32 v[68:69], v[104:105], v[68:69], v[108:109]
	v_pk_fma_f32 v[66:67], v[102:103], v[66:67], v[106:107]
	v_pk_fma_f32 v[4:5], v[68:69], s[60:61], v[4:5] op_sel_hi:[1,0,1]
	v_pk_fma_f32 v[2:3], v[66:67], s[60:61], v[2:3] op_sel_hi:[1,0,1]
	global_store_dwordx4 v194, v[2:5], vcc offset:576
	s_and_b64 vcc, exec, s[40:41]
	s_cbranch_vccz .LBB0_634
	s_waitcnt vmcnt(0)
	s_cmpk_gt_u32 s29, 0xff
	s_cbranch_scc1 .LBB0_649
	s_barrier

.LBB0_660:
	s_add_u32 s48, s46, 0xfffc0080
	s_addc_u32 s49, s47, -1
	s_add_i32 s87, 0, 0x10000
	v_add_u32_e32 v156, s87, v145
	ds_read_b128 v[140:143], v156
	ds_read_b128 v[148:151], v156 offset:1024
	ds_read_b128 v[152:155], v156 offset:2048
	ds_read_b128 v[156:159], v156 offset:3072
	s_cmp_eq_u32 s86, 12
	s_cselect_b32 s63, s15, s49
	s_cselect_b32 s62, s82, s48
	s_cselect_b32 s49, s9, s85
	s_cselect_b32 s48, s83, s84
	v_lshl_add_u64 v[192:193], s[46:47], 0, v[138:139]
	s_add_i32 m0, s45, 0xc000
	ds_read_b128 v[160:163], v147
	ds_read_b128 v[164:167], v147 offset:1024
	ds_read_b128 v[168:171], v147 offset:2048
	ds_read_b128 v[172:175], v147 offset:3072
	ds_read_b128 v[176:179], v147 offset:4096
	ds_read_b128 v[180:183], v147 offset:5120
	ds_read_b128 v[184:187], v147 offset:6144
	ds_read_b128 v[188:191], v147 offset:7168
	global_load_lds_dwordx4 v[192:193], off
	v_lshl_add_u64 v[192:193], s[46:47], 0, v[136:137]
	s_add_i32 m0, s45, 0xe000
	s_nop 0
	global_load_lds_dwordx4 v[192:193], off
	s_waitcnt lgkmcnt(8)
	s_barrier
	s_waitcnt lgkmcnt(0)
	s_waitcnt lgkmcnt(0)
	v_mfma_f32_16x16x32_bf16 v[126:129], v[140:143], v[160:163], v[126:129]
	v_mfma_f32_16x16x32_bf16 v[122:125], v[152:155], v[160:163], v[122:125]
	v_mfma_f32_16x16x32_bf16 v[110:113], v[140:143], v[168:171], v[110:113]
	v_mfma_f32_16x16x32_bf16 v[106:109], v[152:155], v[168:171], v[106:109]
	v_mfma_f32_16x16x32_bf16 v[94:97], v[140:143], v[176:179], v[94:97]
	v_mfma_f32_16x16x32_bf16 v[90:93], v[152:155], v[176:179], v[90:93]
	v_mfma_f32_16x16x32_bf16 v[78:81], v[140:143], v[184:187], v[78:81]
	v_mfma_f32_16x16x32_bf16 v[74:77], v[152:155], v[184:187], v[74:77]
	v_mfma_f32_16x16x32_bf16 v[126:129], v[148:151], v[164:167], v[126:129]
	v_mfma_f32_16x16x32_bf16 v[122:125], v[156:159], v[164:167], v[122:125]
	v_mfma_f32_16x16x32_bf16 v[110:113], v[148:151], v[172:175], v[110:113]
	v_mfma_f32_16x16x32_bf16 v[106:109], v[156:159], v[172:175], v[106:109]
	v_mfma_f32_16x16x32_bf16 v[94:97], v[148:151], v[180:183], v[94:97]
	v_mfma_f32_16x16x32_bf16 v[90:93], v[156:159], v[180:183], v[90:93]
	v_mfma_f32_16x16x32_bf16 v[78:81], v[148:151], v[188:191], v[78:81]
	v_mfma_f32_16x16x32_bf16 v[74:77], v[156:159], v[188:191], v[74:77]
	s_barrier
	s_add_i32 s90, 0, 0x14000
	v_add_u32_e32 v192, s90, v145
	s_add_i32 s87, s87, s66
	ds_read_b128 v[196:199], v192
	ds_read_b128 v[204:207], v192 offset:1024
	ds_read_b128 v[208:211], v192 offset:2048
	ds_read_b128 v[212:215], v192 offset:3072
	v_lshl_add_u64 v[192:193], s[48:49], 0, v[0:1]
	s_mov_b32 m0, s87
	v_lshl_add_u64 v[200:201], s[48:49], 0, v[130:131]
	global_load_lds_dwordx4 v[192:193], off
	s_add_i32 m0, s87, 0x2000
	s_nop 0
	global_load_lds_dwordx4 v[200:201], off
	s_barrier
	s_waitcnt lgkmcnt(0)
	s_waitcnt lgkmcnt(0)
	v_mfma_f32_16x16x32_bf16 v[118:121], v[196:199], v[160:163], v[118:121]
	v_mfma_f32_16x16x32_bf16 v[114:117], v[208:211], v[160:163], v[114:117]
	v_mfma_f32_16x16x32_bf16 v[102:105], v[196:199], v[168:171], v[102:105]
	v_mfma_f32_16x16x32_bf16 v[98:101], v[208:211], v[168:171], v[98:101]
	v_mfma_f32_16x16x32_bf16 v[86:89], v[196:199], v[176:179], v[86:89]
	v_mfma_f32_16x16x32_bf16 v[82:85], v[208:211], v[176:179], v[82:85]
	v_mfma_f32_16x16x32_bf16 v[70:73], v[196:199], v[184:187], v[70:73]
	v_mfma_f32_16x16x32_bf16 v[66:69], v[208:211], v[184:187], v[66:69]
	v_mfma_f32_16x16x32_bf16 v[118:121], v[204:207], v[164:167], v[118:121]
	v_mfma_f32_16x16x32_bf16 v[114:117], v[212:215], v[164:167], v[114:117]
	v_mfma_f32_16x16x32_bf16 v[102:105], v[204:207], v[172:175], v[102:105]
	v_mfma_f32_16x16x32_bf16 v[98:101], v[212:215], v[172:175], v[98:101]
	v_mfma_f32_16x16x32_bf16 v[86:89], v[204:207], v[180:183], v[86:89]
	v_mfma_f32_16x16x32_bf16 v[82:85], v[212:215], v[180:183], v[82:85]
	v_mfma_f32_16x16x32_bf16 v[70:73], v[204:207], v[188:191], v[70:73]
	v_mfma_f32_16x16x32_bf16 v[66:69], v[212:215], v[188:191], v[66:69]
	s_mov_b32 m0, s45
	v_lshl_add_u64 v[202:203], s[62:63], 0, v[134:135]
	s_barrier
	ds_read_b128 v[160:163], v147 offset:16384
	ds_read_b128 v[164:167], v147 offset:17408
	ds_read_b128 v[168:171], v147 offset:18432
	ds_read_b128 v[172:175], v147 offset:19456
	ds_read_b128 v[176:179], v147 offset:20480
	ds_read_b128 v[180:183], v147 offset:21504
	ds_read_b128 v[184:187], v147 offset:22528
	ds_read_b128 v[188:191], v147 offset:23552
	global_load_lds_dwordx4 v[202:203], off
	v_lshl_add_u64 v[216:217], s[62:63], 0, v[132:133]
	s_mov_b32 m0, s68
	s_nop 0
	global_load_lds_dwordx4 v[216:217], off
	s_barrier
	s_waitcnt lgkmcnt(0)
	s_waitcnt lgkmcnt(0)
	v_mfma_f32_16x16x32_bf16 v[62:65], v[140:143], v[160:163], v[62:65]
	v_mfma_f32_16x16x32_bf16 v[58:61], v[152:155], v[160:163], v[58:61]
	v_mfma_f32_16x16x32_bf16 v[46:49], v[140:143], v[168:171], v[46:49]
	v_mfma_f32_16x16x32_bf16 v[42:45], v[152:155], v[168:171], v[42:45]
	v_mfma_f32_16x16x32_bf16 v[30:33], v[140:143], v[176:179], v[30:33]
	v_mfma_f32_16x16x32_bf16 v[26:29], v[152:155], v[176:179], v[26:29]
	v_mfma_f32_16x16x32_bf16 v[14:17], v[140:143], v[184:187], v[14:17]
	v_mfma_f32_16x16x32_bf16 v[10:13], v[152:155], v[184:187], v[10:13]
	v_mfma_f32_16x16x32_bf16 v[62:65], v[148:151], v[164:167], v[62:65]
	v_mfma_f32_16x16x32_bf16 v[58:61], v[156:159], v[164:167], v[58:61]
	v_mfma_f32_16x16x32_bf16 v[46:49], v[148:151], v[172:175], v[46:49]
	v_mfma_f32_16x16x32_bf16 v[42:45], v[156:159], v[172:175], v[42:45]
	v_mfma_f32_16x16x32_bf16 v[30:33], v[148:151], v[180:183], v[30:33]
	v_mfma_f32_16x16x32_bf16 v[26:29], v[156:159], v[180:183], v[26:29]
	v_mfma_f32_16x16x32_bf16 v[14:17], v[148:151], v[188:191], v[14:17]
	v_mfma_f32_16x16x32_bf16 v[10:13], v[156:159], v[188:191], v[10:13]
	s_barrier
	s_add_u32 s88, s48, 0x40000
	s_addc_u32 s89, s49, 0
	s_add_i32 s87, s90, s66
	v_lshl_add_u64 v[140:141], s[88:89], 0, v[0:1]
	s_mov_b32 m0, s87
	s_nop 0
	global_load_lds_dwordx4 v[140:141], off
	v_lshl_add_u64 v[140:141], s[88:89], 0, v[130:131]
	s_add_i32 m0, s87, 0x2000
	s_nop 0
	global_load_lds_dwordx4 v[140:141], off
	s_waitcnt vmcnt(6)
	s_barrier
	v_mfma_f32_16x16x32_bf16 v[54:57], v[196:199], v[160:163], v[54:57]
	v_mfma_f32_16x16x32_bf16 v[50:53], v[208:211], v[160:163], v[50:53]
	v_mfma_f32_16x16x32_bf16 v[38:41], v[196:199], v[168:171], v[38:41]
	v_mfma_f32_16x16x32_bf16 v[34:37], v[208:211], v[168:171], v[34:37]
	v_mfma_f32_16x16x32_bf16 v[22:25], v[196:199], v[176:179], v[22:25]
	v_mfma_f32_16x16x32_bf16 v[18:21], v[208:211], v[176:179], v[18:21]
	v_mfma_f32_16x16x32_bf16 v[6:9], v[196:199], v[184:187], v[6:9]
	v_mfma_f32_16x16x32_bf16 v[2:5], v[208:211], v[184:187], v[2:5]
	v_mfma_f32_16x16x32_bf16 v[54:57], v[204:207], v[164:167], v[54:57]
	v_mfma_f32_16x16x32_bf16 v[50:53], v[212:215], v[164:167], v[50:53]
	v_mfma_f32_16x16x32_bf16 v[38:41], v[204:207], v[172:175], v[38:41]
	v_mfma_f32_16x16x32_bf16 v[34:37], v[212:215], v[172:175], v[34:37]
	v_mfma_f32_16x16x32_bf16 v[22:25], v[204:207], v[180:183], v[22:25]
	v_mfma_f32_16x16x32_bf16 v[18:21], v[212:215], v[180:183], v[18:21]
	v_mfma_f32_16x16x32_bf16 v[6:9], v[204:207], v[188:191], v[6:9]
	v_mfma_f32_16x16x32_bf16 v[2:5], v[212:215], v[188:191], v[2:5]
	s_add_i32 s87, 0, 0x18000
	v_add_u32_e32 v156, s87, v145
	s_barrier
	ds_read_b128 v[140:143], v156
	ds_read_b128 v[148:151], v156 offset:1024
	ds_read_b128 v[152:155], v156 offset:2048
	ds_read_b128 v[156:159], v156 offset:3072
	s_add_u32 s62, s62, 0x40000
	s_addc_u32 s63, s63, 0
	s_mov_b32 m0, s69
	v_lshl_add_u64 v[196:197], s[62:63], 0, v[134:135]
	ds_read_b128 v[160:163], v147 offset:32768
	ds_read_b128 v[164:167], v147 offset:33792
	ds_read_b128 v[168:171], v147 offset:34816
	ds_read_b128 v[172:175], v147 offset:35840
	ds_read_b128 v[176:179], v147 offset:36864
	ds_read_b128 v[180:183], v147 offset:37888
	ds_read_b128 v[184:187], v147 offset:38912
	ds_read_b128 v[188:191], v147 offset:39936
	global_load_lds_dwordx4 v[196:197], off
	v_lshl_add_u64 v[196:197], s[62:63], 0, v[132:133]
	s_mov_b32 m0, s70
	s_nop 0
	global_load_lds_dwordx4 v[196:197], off
	s_waitcnt lgkmcnt(8)
	s_barrier
	s_waitcnt lgkmcnt(0)
	s_waitcnt lgkmcnt(0)
	v_mfma_f32_16x16x32_bf16 v[126:129], v[140:143], v[160:163], v[126:129]
	v_mfma_f32_16x16x32_bf16 v[122:125], v[152:155], v[160:163], v[122:125]
	v_mfma_f32_16x16x32_bf16 v[110:113], v[140:143], v[168:171], v[110:113]
	v_mfma_f32_16x16x32_bf16 v[106:109], v[152:155], v[168:171], v[106:109]
	v_mfma_f32_16x16x32_bf16 v[94:97], v[140:143], v[176:179], v[94:97]
	v_mfma_f32_16x16x32_bf16 v[90:93], v[152:155], v[176:179], v[90:93]
	v_mfma_f32_16x16x32_bf16 v[78:81], v[140:143], v[184:187], v[78:81]
	v_mfma_f32_16x16x32_bf16 v[74:77], v[152:155], v[184:187], v[74:77]
	v_mfma_f32_16x16x32_bf16 v[126:129], v[148:151], v[164:167], v[126:129]
	v_mfma_f32_16x16x32_bf16 v[122:125], v[156:159], v[164:167], v[122:125]
	v_mfma_f32_16x16x32_bf16 v[110:113], v[148:151], v[172:175], v[110:113]
	v_mfma_f32_16x16x32_bf16 v[106:109], v[156:159], v[172:175], v[106:109]
	v_mfma_f32_16x16x32_bf16 v[94:97], v[148:151], v[180:183], v[94:97]
	v_mfma_f32_16x16x32_bf16 v[90:93], v[156:159], v[180:183], v[90:93]
	v_mfma_f32_16x16x32_bf16 v[78:81], v[148:151], v[188:191], v[78:81]
	v_mfma_f32_16x16x32_bf16 v[74:77], v[156:159], v[188:191], v[74:77]
	s_barrier
	s_add_i32 s62, 0, 0x1c000
	s_add_i32 s63, s87, s66
	v_add_u32_e32 v194, s62, v145
	v_lshl_add_u64 v[192:193], v[192:193], 0, s[12:13]
	s_mov_b32 m0, s63
	ds_read_b128 v[196:199], v194
	ds_read_b128 v[204:207], v194 offset:1024
	ds_read_b128 v[208:211], v194 offset:2048
	ds_read_b128 v[212:215], v194 offset:3072
	global_load_lds_dwordx4 v[192:193], off
	v_lshl_add_u64 v[192:193], v[200:201], 0, s[12:13]
	s_add_i32 m0, s63, 0x2000
	s_nop 0
	global_load_lds_dwordx4 v[192:193], off
	s_barrier
	s_waitcnt lgkmcnt(0)
	s_waitcnt lgkmcnt(0)
	v_mfma_f32_16x16x32_bf16 v[118:121], v[196:199], v[160:163], v[118:121]
	v_mfma_f32_16x16x32_bf16 v[114:117], v[208:211], v[160:163], v[114:117]
	v_mfma_f32_16x16x32_bf16 v[102:105], v[196:199], v[168:171], v[102:105]
	v_mfma_f32_16x16x32_bf16 v[98:101], v[208:211], v[168:171], v[98:101]
	v_mfma_f32_16x16x32_bf16 v[86:89], v[196:199], v[176:179], v[86:89]
	v_mfma_f32_16x16x32_bf16 v[82:85], v[208:211], v[176:179], v[82:85]
	v_mfma_f32_16x16x32_bf16 v[70:73], v[196:199], v[184:187], v[70:73]
	v_mfma_f32_16x16x32_bf16 v[66:69], v[208:211], v[184:187], v[66:69]
	v_mfma_f32_16x16x32_bf16 v[118:121], v[204:207], v[164:167], v[118:121]
	v_mfma_f32_16x16x32_bf16 v[114:117], v[212:215], v[164:167], v[114:117]
	v_mfma_f32_16x16x32_bf16 v[102:105], v[204:207], v[172:175], v[102:105]
	v_mfma_f32_16x16x32_bf16 v[98:101], v[212:215], v[172:175], v[98:101]
	v_mfma_f32_16x16x32_bf16 v[86:89], v[204:207], v[180:183], v[86:89]
	v_mfma_f32_16x16x32_bf16 v[82:85], v[212:215], v[180:183], v[82:85]
	v_mfma_f32_16x16x32_bf16 v[70:73], v[204:207], v[188:191], v[70:73]
	v_mfma_f32_16x16x32_bf16 v[66:69], v[212:215], v[188:191], v[66:69]
	s_mov_b32 m0, s71
	v_lshl_add_u64 v[192:193], v[202:203], 0, s[12:13]
	s_barrier
	ds_read_b128 v[160:163], v147 offset:49152
	ds_read_b128 v[164:167], v147 offset:50176
	ds_read_b128 v[168:171], v147 offset:51200
	ds_read_b128 v[172:175], v147 offset:52224
	ds_read_b128 v[176:179], v147 offset:53248
	ds_read_b128 v[180:183], v147 offset:54272
	ds_read_b128 v[184:187], v147 offset:55296
	ds_read_b128 v[188:191], v147 offset:56320
	global_load_lds_dwordx4 v[192:193], off
	v_lshl_add_u64 v[192:193], v[216:217], 0, s[12:13]
	s_mov_b32 m0, s78
	s_nop 0
	global_load_lds_dwordx4 v[192:193], off
	s_barrier
	s_waitcnt lgkmcnt(0)
	s_waitcnt lgkmcnt(0)
	v_mfma_f32_16x16x32_bf16 v[62:65], v[140:143], v[160:163], v[62:65]
	v_mfma_f32_16x16x32_bf16 v[58:61], v[152:155], v[160:163], v[58:61]
	v_mfma_f32_16x16x32_bf16 v[46:49], v[140:143], v[168:171], v[46:49]
	v_mfma_f32_16x16x32_bf16 v[42:45], v[152:155], v[168:171], v[42:45]
	v_mfma_f32_16x16x32_bf16 v[30:33], v[140:143], v[176:179], v[30:33]
	v_mfma_f32_16x16x32_bf16 v[26:29], v[152:155], v[176:179], v[26:29]
	v_mfma_f32_16x16x32_bf16 v[14:17], v[140:143], v[184:187], v[14:17]
	v_mfma_f32_16x16x32_bf16 v[10:13], v[152:155], v[184:187], v[10:13]
	v_mfma_f32_16x16x32_bf16 v[62:65], v[148:151], v[164:167], v[62:65]
	v_mfma_f32_16x16x32_bf16 v[58:61], v[156:159], v[164:167], v[58:61]
	v_mfma_f32_16x16x32_bf16 v[46:49], v[148:151], v[172:175], v[46:49]
	v_mfma_f32_16x16x32_bf16 v[42:45], v[156:159], v[172:175], v[42:45]
	v_mfma_f32_16x16x32_bf16 v[30:33], v[148:151], v[180:183], v[30:33]
	v_mfma_f32_16x16x32_bf16 v[26:29], v[156:159], v[180:183], v[26:29]
	v_mfma_f32_16x16x32_bf16 v[14:17], v[148:151], v[188:191], v[14:17]
	v_mfma_f32_16x16x32_bf16 v[10:13], v[156:159], v[188:191], v[10:13]
	s_barrier
	s_add_u32 s48, s48, 0x40080
	s_addc_u32 s49, s49, 0
	s_add_i32 s62, s62, s66
	v_lshl_add_u64 v[140:141], s[48:49], 0, v[0:1]
	s_mov_b32 m0, s62
	s_nop 0
	global_load_lds_dwordx4 v[140:141], off
	v_lshl_add_u64 v[140:141], s[48:49], 0, v[130:131]
	s_add_i32 m0, s62, 0x2000
	s_nop 0
	global_load_lds_dwordx4 v[140:141], off
	s_waitcnt vmcnt(6)
	s_barrier
	v_mfma_f32_16x16x32_bf16 v[54:57], v[196:199], v[160:163], v[54:57]
	v_mfma_f32_16x16x32_bf16 v[50:53], v[208:211], v[160:163], v[50:53]
	v_mfma_f32_16x16x32_bf16 v[38:41], v[196:199], v[168:171], v[38:41]
	v_mfma_f32_16x16x32_bf16 v[34:37], v[208:211], v[168:171], v[34:37]
	v_mfma_f32_16x16x32_bf16 v[22:25], v[196:199], v[176:179], v[22:25]
	v_mfma_f32_16x16x32_bf16 v[18:21], v[208:211], v[176:179], v[18:21]
	v_mfma_f32_16x16x32_bf16 v[6:9], v[196:199], v[184:187], v[6:9]
	v_mfma_f32_16x16x32_bf16 v[2:5], v[208:211], v[184:187], v[2:5]
	v_mfma_f32_16x16x32_bf16 v[54:57], v[204:207], v[164:167], v[54:57]
	v_mfma_f32_16x16x32_bf16 v[50:53], v[212:215], v[164:167], v[50:53]
	v_mfma_f32_16x16x32_bf16 v[38:41], v[204:207], v[172:175], v[38:41]
	v_mfma_f32_16x16x32_bf16 v[34:37], v[212:215], v[172:175], v[34:37]
	v_mfma_f32_16x16x32_bf16 v[22:25], v[204:207], v[180:183], v[22:25]
	v_mfma_f32_16x16x32_bf16 v[18:21], v[212:215], v[180:183], v[18:21]
	v_mfma_f32_16x16x32_bf16 v[6:9], v[204:207], v[188:191], v[6:9]
	v_mfma_f32_16x16x32_bf16 v[2:5], v[212:215], v[188:191], v[2:5]
	s_add_i32 s86, s86, 2
	s_add_u32 s84, s84, 0x100
	s_addc_u32 s85, s85, 0
	s_add_u32 s46, s46, 0x100
	s_addc_u32 s47, s47, 0
	s_cmp_gt_u32 s86, 13
	s_barrier
	s_cbranch_scc0 .LBB0_660
	v_mul_f32_e32 v140, 0xbfb8aa3b, v126
	v_exp_f32_e32 v140, v140
	v_lshl_or_b32 v142, s81, 7, v146
	v_lshl_add_u32 v148, s44, 8, v144
	v_ashrrev_i32_e32 v143, 31, v142
	v_add_f32_e32 v140, 1.0, v140
	v_rcp_f32_e32 v150, v140
	v_mul_f32_e32 v140, 0xbfb8aa3b, v127
	v_exp_f32_e32 v140, v140
	s_movk_i32 s9, 0x1600
	v_lshlrev_b64 v[142:143], 1, v[142:143]
	s_and_b64 vcc, exec, s[40:41]
	v_add_f32_e32 v140, 1.0, v140
	v_rcp_f32_e32 v151, v140
	v_mul_f32_e32 v140, 0xbfb8aa3b, v128
	v_exp_f32_e32 v140, v140
	s_mov_b32 s81, s8
	v_pk_mul_f32 v[126:127], v[126:127], v[150:151]
	s_mov_b32 s44, s14
	v_add_f32_e32 v140, 1.0, v140
	v_rcp_f32_e32 v152, v140
	v_mul_f32_e32 v140, 0xbfb8aa3b, v129
	v_exp_f32_e32 v140, v140
	v_pk_mul_f32 v[118:119], v[126:127], v[118:119]
	s_mov_b64 s[48:49], s[16:17]
	v_cvt_pk_bf16_f32 v118, v118, v119
	v_add_f32_e32 v140, 1.0, v140
	v_rcp_f32_e32 v153, v140
	v_mul_f32_e32 v140, 0xbfb8aa3b, v122
	v_exp_f32_e32 v140, v140
	v_pk_mul_f32 v[126:127], v[128:129], v[152:153]
	s_nop 0
	v_pk_mul_f32 v[120:121], v[126:127], v[120:121]
	v_add_f32_e32 v140, 1.0, v140
	v_rcp_f32_e32 v154, v140
	v_mul_f32_e32 v140, 0xbfb8aa3b, v123
	v_exp_f32_e32 v140, v140
	v_cvt_pk_bf16_f32 v119, v120, v121
	v_add_f32_e32 v140, 1.0, v140
	v_rcp_f32_e32 v155, v140
	v_mul_f32_e32 v140, 0xbfb8aa3b, v124
	v_exp_f32_e32 v140, v140
	v_pk_mul_f32 v[120:121], v[122:123], v[154:155]
	s_nop 0
	v_pk_mul_f32 v[114:115], v[120:121], v[114:115]
	v_add_f32_e32 v140, 1.0, v140
	v_rcp_f32_e32 v156, v140
	v_mul_f32_e32 v140, 0xbfb8aa3b, v125
	v_exp_f32_e32 v140, v140
	v_cvt_pk_bf16_f32 v120, v114, v115
	v_or_b32_e32 v122, 16, v148
	v_add_f32_e32 v140, 1.0, v140
	v_rcp_f32_e32 v157, v140
	v_mov_b64_e32 v[140:141], s[4:5]
	v_mad_i64_i32 v[158:159], s[46:47], v148, s9, v[140:141]
	v_pk_mul_f32 v[114:115], v[124:125], v[156:157]
	v_lshl_add_u64 v[158:159], v[158:159], 0, v[142:143]
	v_pk_mul_f32 v[114:115], v[114:115], v[116:117]
	v_mul_f32_e32 v116, 0xbfb8aa3b, v112
	v_cvt_pk_bf16_f32 v121, v114, v115
	v_mul_f32_e32 v114, 0xbfb8aa3b, v110
	v_mul_f32_e32 v115, 0xbfb8aa3b, v111
	v_exp_f32_e32 v114, v114
	v_exp_f32_e32 v115, v115
	v_mul_f32_e32 v117, 0xbfb8aa3b, v113
	v_exp_f32_e32 v116, v116
	v_exp_f32_e32 v117, v117
	global_store_dwordx4 v[158:159], v[118:121], off
	v_add_f32_e32 v114, 1.0, v114
	v_add_f32_e32 v115, 1.0, v115
	v_mul_f32_e32 v118, 0xbfb8aa3b, v106
	v_mul_f32_e32 v119, 0xbfb8aa3b, v107
	v_exp_f32_e32 v118, v118
	v_exp_f32_e32 v119, v119
	v_mul_f32_e32 v120, 0xbfb8aa3b, v108
	v_mul_f32_e32 v121, 0xbfb8aa3b, v109
	v_rcp_f32_e32 v114, v114
	v_rcp_f32_e32 v115, v115
	v_add_f32_e32 v116, 1.0, v116
	v_add_f32_e32 v117, 1.0, v117
	v_exp_f32_e32 v120, v120
	v_exp_f32_e32 v121, v121
	v_rcp_f32_e32 v116, v116
	v_rcp_f32_e32 v117, v117
	v_add_f32_e32 v118, 1.0, v118
	v_add_f32_e32 v119, 1.0, v119
	v_rcp_f32_e32 v118, v118
	v_rcp_f32_e32 v119, v119
	v_add_f32_e32 v120, 1.0, v120
	v_add_f32_e32 v121, 1.0, v121
	v_pk_mul_f32 v[110:111], v[110:111], v[114:115]
	v_rcp_f32_e32 v120, v120
	v_rcp_f32_e32 v121, v121
	v_pk_mul_f32 v[102:103], v[110:111], v[102:103]
	v_pk_mul_f32 v[110:111], v[112:113], v[116:117]
	v_cvt_pk_bf16_f32 v102, v102, v103
	v_pk_mul_f32 v[104:105], v[110:111], v[104:105]
	v_mad_i64_i32 v[122:123], s[46:47], v122, s9, v[140:141]
	v_cvt_pk_bf16_f32 v103, v104, v105
	v_pk_mul_f32 v[104:105], v[106:107], v[118:119]
	v_lshl_add_u64 v[122:123], v[122:123], 0, v[142:143]
	v_pk_mul_f32 v[98:99], v[104:105], v[98:99]
	v_or_b32_e32 v106, 32, v148
	v_cvt_pk_bf16_f32 v104, v98, v99
	v_pk_mul_f32 v[98:99], v[108:109], v[120:121]
	v_mad_i64_i32 v[106:107], s[46:47], v106, s9, v[140:141]
	v_pk_mul_f32 v[98:99], v[98:99], v[100:101]
	v_mul_f32_e32 v100, 0xbfb8aa3b, v96
	v_cvt_pk_bf16_f32 v105, v98, v99
	v_mul_f32_e32 v98, 0xbfb8aa3b, v94
	v_mul_f32_e32 v99, 0xbfb8aa3b, v95
	v_exp_f32_e32 v98, v98
	v_exp_f32_e32 v99, v99
	v_mul_f32_e32 v101, 0xbfb8aa3b, v97
	v_exp_f32_e32 v100, v100
	v_exp_f32_e32 v101, v101
	global_store_dwordx4 v[122:123], v[102:105], off
	v_add_f32_e32 v98, 1.0, v98
	v_add_f32_e32 v99, 1.0, v99
	v_mul_f32_e32 v102, 0xbfb8aa3b, v90
	v_mul_f32_e32 v103, 0xbfb8aa3b, v91
	v_exp_f32_e32 v102, v102
	v_exp_f32_e32 v103, v103
	v_mul_f32_e32 v104, 0xbfb8aa3b, v92
	v_mul_f32_e32 v105, 0xbfb8aa3b, v93
	v_rcp_f32_e32 v98, v98
	v_rcp_f32_e32 v99, v99
	v_add_f32_e32 v100, 1.0, v100
	v_add_f32_e32 v101, 1.0, v101
	v_exp_f32_e32 v104, v104
	v_exp_f32_e32 v105, v105
	v_rcp_f32_e32 v100, v100
	v_rcp_f32_e32 v101, v101
	v_add_f32_e32 v102, 1.0, v102
	v_add_f32_e32 v103, 1.0, v103
	v_rcp_f32_e32 v102, v102
	v_rcp_f32_e32 v103, v103
	v_add_f32_e32 v104, 1.0, v104
	v_add_f32_e32 v105, 1.0, v105
	v_pk_mul_f32 v[94:95], v[94:95], v[98:99]
	v_rcp_f32_e32 v104, v104
	v_rcp_f32_e32 v105, v105
	v_pk_mul_f32 v[86:87], v[94:95], v[86:87]
	v_pk_mul_f32 v[94:95], v[96:97], v[100:101]
	v_cvt_pk_bf16_f32 v86, v86, v87
	v_pk_mul_f32 v[88:89], v[94:95], v[88:89]
	v_lshl_add_u64 v[106:107], v[106:107], 0, v[142:143]
	v_cvt_pk_bf16_f32 v87, v88, v89
	v_pk_mul_f32 v[88:89], v[90:91], v[102:103]
	v_or_b32_e32 v90, 48, v148
	v_pk_mul_f32 v[82:83], v[88:89], v[82:83]
	v_mad_i64_i32 v[90:91], s[46:47], v90, s9, v[140:141]
	v_cvt_pk_bf16_f32 v88, v82, v83
	v_pk_mul_f32 v[82:83], v[92:93], v[104:105]
	v_lshl_add_u64 v[90:91], v[90:91], 0, v[142:143]
	v_pk_mul_f32 v[82:83], v[82:83], v[84:85]
	v_mul_f32_e32 v84, 0xbfb8aa3b, v80
	v_cvt_pk_bf16_f32 v89, v82, v83
	v_mul_f32_e32 v82, 0xbfb8aa3b, v78
	v_mul_f32_e32 v83, 0xbfb8aa3b, v79
	v_exp_f32_e32 v82, v82
	v_exp_f32_e32 v83, v83
	v_mul_f32_e32 v85, 0xbfb8aa3b, v81
	v_exp_f32_e32 v84, v84
	v_exp_f32_e32 v85, v85
	global_store_dwordx4 v[106:107], v[86:89], off
	v_add_f32_e32 v82, 1.0, v82
	v_add_f32_e32 v83, 1.0, v83
	v_mul_f32_e32 v86, 0xbfb8aa3b, v74
	v_mul_f32_e32 v87, 0xbfb8aa3b, v75
	v_exp_f32_e32 v86, v86
	v_exp_f32_e32 v87, v87
	v_mul_f32_e32 v88, 0xbfb8aa3b, v76
	v_mul_f32_e32 v89, 0xbfb8aa3b, v77
	v_rcp_f32_e32 v82, v82
	v_rcp_f32_e32 v83, v83
	v_add_f32_e32 v84, 1.0, v84
	v_add_f32_e32 v85, 1.0, v85
	v_exp_f32_e32 v88, v88
	v_exp_f32_e32 v89, v89
	v_rcp_f32_e32 v84, v84
	v_rcp_f32_e32 v85, v85
	v_add_f32_e32 v86, 1.0, v86
	v_add_f32_e32 v87, 1.0, v87
	v_rcp_f32_e32 v86, v86
	v_rcp_f32_e32 v87, v87
	v_add_f32_e32 v88, 1.0, v88
	v_add_f32_e32 v89, 1.0, v89
	v_pk_mul_f32 v[78:79], v[78:79], v[82:83]
	v_rcp_f32_e32 v88, v88
	v_rcp_f32_e32 v89, v89
	v_pk_mul_f32 v[70:71], v[78:79], v[70:71]
	v_pk_mul_f32 v[78:79], v[80:81], v[84:85]
	v_cvt_pk_bf16_f32 v70, v70, v71
	v_pk_mul_f32 v[72:73], v[78:79], v[72:73]
	s_nop 0
	v_cvt_pk_bf16_f32 v71, v72, v73
	v_pk_mul_f32 v[72:73], v[74:75], v[86:87]
	v_add_u32_e32 v74, 0x80, v148
	v_pk_mul_f32 v[66:67], v[72:73], v[66:67]
	v_mad_i64_i32 v[74:75], s[46:47], v74, s9, v[140:141]
	v_cvt_pk_bf16_f32 v72, v66, v67
	v_pk_mul_f32 v[66:67], v[76:77], v[88:89]
	v_lshl_add_u64 v[74:75], v[74:75], 0, v[142:143]
	v_pk_mul_f32 v[66:67], v[66:67], v[68:69]
	v_mul_f32_e32 v68, 0xbfb8aa3b, v64
	v_cvt_pk_bf16_f32 v73, v66, v67
	v_mul_f32_e32 v66, 0xbfb8aa3b, v62
	v_mul_f32_e32 v67, 0xbfb8aa3b, v63
	v_exp_f32_e32 v66, v66
	v_exp_f32_e32 v67, v67
	v_mul_f32_e32 v69, 0xbfb8aa3b, v65
	v_exp_f32_e32 v68, v68
	v_exp_f32_e32 v69, v69
	global_store_dwordx4 v[90:91], v[70:73], off
	v_add_f32_e32 v66, 1.0, v66
	v_add_f32_e32 v67, 1.0, v67
	v_mul_f32_e32 v70, 0xbfb8aa3b, v58
	v_mul_f32_e32 v71, 0xbfb8aa3b, v59
	v_exp_f32_e32 v70, v70
	v_exp_f32_e32 v71, v71
	v_mul_f32_e32 v72, 0xbfb8aa3b, v60
	v_mul_f32_e32 v73, 0xbfb8aa3b, v61
	v_rcp_f32_e32 v66, v66
	v_rcp_f32_e32 v67, v67
	v_add_f32_e32 v68, 1.0, v68
	v_add_f32_e32 v69, 1.0, v69
	v_exp_f32_e32 v72, v72
	v_exp_f32_e32 v73, v73
	v_rcp_f32_e32 v68, v68
	v_rcp_f32_e32 v69, v69
	v_add_f32_e32 v70, 1.0, v70
	v_add_f32_e32 v71, 1.0, v71
	v_rcp_f32_e32 v70, v70
	v_rcp_f32_e32 v71, v71
	v_add_f32_e32 v72, 1.0, v72
	v_add_f32_e32 v73, 1.0, v73
	v_pk_mul_f32 v[62:63], v[62:63], v[66:67]
	v_rcp_f32_e32 v72, v72
	v_rcp_f32_e32 v73, v73
	v_pk_mul_f32 v[54:55], v[62:63], v[54:55]
	v_pk_mul_f32 v[62:63], v[64:65], v[68:69]
	v_cvt_pk_bf16_f32 v54, v54, v55
	v_pk_mul_f32 v[56:57], v[62:63], v[56:57]
	s_nop 0
	v_cvt_pk_bf16_f32 v55, v56, v57
	v_pk_mul_f32 v[56:57], v[58:59], v[70:71]
	v_add_u32_e32 v58, 0x90, v148
	v_pk_mul_f32 v[50:51], v[56:57], v[50:51]
	v_mad_i64_i32 v[58:59], s[46:47], v58, s9, v[140:141]
	v_cvt_pk_bf16_f32 v56, v50, v51
	v_pk_mul_f32 v[50:51], v[60:61], v[72:73]
	v_lshl_add_u64 v[58:59], v[58:59], 0, v[142:143]
	v_pk_mul_f32 v[50:51], v[50:51], v[52:53]
	v_mul_f32_e32 v52, 0xbfb8aa3b, v48
	v_cvt_pk_bf16_f32 v57, v50, v51
	v_mul_f32_e32 v50, 0xbfb8aa3b, v46
	v_mul_f32_e32 v51, 0xbfb8aa3b, v47
	v_exp_f32_e32 v50, v50
	v_exp_f32_e32 v51, v51
	v_mul_f32_e32 v53, 0xbfb8aa3b, v49
	v_exp_f32_e32 v52, v52
	v_exp_f32_e32 v53, v53
	global_store_dwordx4 v[74:75], v[54:57], off
	v_add_f32_e32 v50, 1.0, v50
	v_add_f32_e32 v51, 1.0, v51
	v_mul_f32_e32 v54, 0xbfb8aa3b, v42
	v_mul_f32_e32 v55, 0xbfb8aa3b, v43
	v_exp_f32_e32 v54, v54
	v_exp_f32_e32 v55, v55
	v_mul_f32_e32 v56, 0xbfb8aa3b, v44
	v_mul_f32_e32 v57, 0xbfb8aa3b, v45
	v_rcp_f32_e32 v50, v50
	v_rcp_f32_e32 v51, v51
	v_add_f32_e32 v52, 1.0, v52
	v_add_f32_e32 v53, 1.0, v53
	v_exp_f32_e32 v56, v56
	v_exp_f32_e32 v57, v57
	v_rcp_f32_e32 v52, v52
	v_rcp_f32_e32 v53, v53
	v_add_f32_e32 v54, 1.0, v54
	v_add_f32_e32 v55, 1.0, v55
	v_rcp_f32_e32 v54, v54
	v_rcp_f32_e32 v55, v55
	v_add_f32_e32 v56, 1.0, v56
	v_add_f32_e32 v57, 1.0, v57
	v_pk_mul_f32 v[46:47], v[46:47], v[50:51]
	v_rcp_f32_e32 v56, v56
	v_rcp_f32_e32 v57, v57
	v_pk_mul_f32 v[38:39], v[46:47], v[38:39]
	v_pk_mul_f32 v[46:47], v[48:49], v[52:53]
	v_cvt_pk_bf16_f32 v38, v38, v39
	v_pk_mul_f32 v[40:41], v[46:47], v[40:41]
	s_nop 0
	v_cvt_pk_bf16_f32 v39, v40, v41
	v_pk_mul_f32 v[40:41], v[42:43], v[54:55]
	v_add_u32_e32 v42, 0xa0, v148
	v_pk_mul_f32 v[34:35], v[40:41], v[34:35]
	v_mad_i64_i32 v[42:43], s[46:47], v42, s9, v[140:141]
	v_cvt_pk_bf16_f32 v40, v34, v35
	v_pk_mul_f32 v[34:35], v[44:45], v[56:57]
	v_lshl_add_u64 v[42:43], v[42:43], 0, v[142:143]
	v_pk_mul_f32 v[34:35], v[34:35], v[36:37]
	v_mul_f32_e32 v36, 0xbfb8aa3b, v32
	v_cvt_pk_bf16_f32 v41, v34, v35
	v_mul_f32_e32 v34, 0xbfb8aa3b, v30
	v_mul_f32_e32 v35, 0xbfb8aa3b, v31
	v_exp_f32_e32 v34, v34
	v_exp_f32_e32 v35, v35
	v_mul_f32_e32 v37, 0xbfb8aa3b, v33
	v_exp_f32_e32 v36, v36
	v_exp_f32_e32 v37, v37
	global_store_dwordx4 v[58:59], v[38:41], off
	v_add_f32_e32 v34, 1.0, v34
	v_add_f32_e32 v35, 1.0, v35
	v_mul_f32_e32 v38, 0xbfb8aa3b, v26
	v_mul_f32_e32 v39, 0xbfb8aa3b, v27
	v_exp_f32_e32 v38, v38
	v_exp_f32_e32 v39, v39
	v_mul_f32_e32 v40, 0xbfb8aa3b, v28
	v_mul_f32_e32 v41, 0xbfb8aa3b, v29
	v_rcp_f32_e32 v34, v34
	v_rcp_f32_e32 v35, v35
	v_add_f32_e32 v36, 1.0, v36
	v_add_f32_e32 v37, 1.0, v37
	v_exp_f32_e32 v40, v40
	v_exp_f32_e32 v41, v41
	v_rcp_f32_e32 v36, v36
	v_rcp_f32_e32 v37, v37
	v_add_f32_e32 v38, 1.0, v38
	v_add_f32_e32 v39, 1.0, v39
	v_rcp_f32_e32 v38, v38
	v_rcp_f32_e32 v39, v39
	v_add_f32_e32 v40, 1.0, v40
	v_add_f32_e32 v41, 1.0, v41
	v_pk_mul_f32 v[30:31], v[30:31], v[34:35]
	v_rcp_f32_e32 v40, v40
	v_rcp_f32_e32 v41, v41
	v_pk_mul_f32 v[22:23], v[30:31], v[22:23]
	v_pk_mul_f32 v[30:31], v[32:33], v[36:37]
	v_cvt_pk_bf16_f32 v22, v22, v23
	v_pk_mul_f32 v[24:25], v[30:31], v[24:25]
	s_nop 0
	v_cvt_pk_bf16_f32 v23, v24, v25
	v_pk_mul_f32 v[24:25], v[26:27], v[38:39]
	v_add_u32_e32 v26, 0xb0, v148
	v_pk_mul_f32 v[18:19], v[24:25], v[18:19]
	v_mad_i64_i32 v[26:27], s[46:47], v26, s9, v[140:141]
	v_cvt_pk_bf16_f32 v24, v18, v19
	v_pk_mul_f32 v[18:19], v[28:29], v[40:41]
	v_lshl_add_u64 v[26:27], v[26:27], 0, v[142:143]
	v_pk_mul_f32 v[18:19], v[18:19], v[20:21]
	v_mul_f32_e32 v20, 0xbfb8aa3b, v16
	v_cvt_pk_bf16_f32 v25, v18, v19
	v_mul_f32_e32 v18, 0xbfb8aa3b, v14
	v_mul_f32_e32 v19, 0xbfb8aa3b, v15
	v_exp_f32_e32 v18, v18
	v_exp_f32_e32 v19, v19
	v_mul_f32_e32 v21, 0xbfb8aa3b, v17
	v_exp_f32_e32 v20, v20
	v_exp_f32_e32 v21, v21
	global_store_dwordx4 v[42:43], v[22:25], off
	v_add_f32_e32 v18, 1.0, v18
	v_add_f32_e32 v19, 1.0, v19
	v_mul_f32_e32 v22, 0xbfb8aa3b, v10
	v_mul_f32_e32 v23, 0xbfb8aa3b, v11
	v_exp_f32_e32 v22, v22
	v_exp_f32_e32 v23, v23
	v_mul_f32_e32 v24, 0xbfb8aa3b, v12
	v_mul_f32_e32 v25, 0xbfb8aa3b, v13
	v_rcp_f32_e32 v18, v18
	v_rcp_f32_e32 v19, v19
	v_add_f32_e32 v20, 1.0, v20
	v_add_f32_e32 v21, 1.0, v21
	v_exp_f32_e32 v24, v24
	v_exp_f32_e32 v25, v25
	v_rcp_f32_e32 v20, v20
	v_rcp_f32_e32 v21, v21
	v_add_f32_e32 v22, 1.0, v22
	v_add_f32_e32 v23, 1.0, v23
	v_rcp_f32_e32 v22, v22
	v_rcp_f32_e32 v23, v23
	v_add_f32_e32 v24, 1.0, v24
	v_add_f32_e32 v25, 1.0, v25
	v_pk_mul_f32 v[14:15], v[14:15], v[18:19]
	v_rcp_f32_e32 v24, v24
	v_rcp_f32_e32 v25, v25
	v_pk_mul_f32 v[6:7], v[14:15], v[6:7]
	v_pk_mul_f32 v[14:15], v[16:17], v[20:21]
	v_cvt_pk_bf16_f32 v6, v6, v7
	v_pk_mul_f32 v[8:9], v[14:15], v[8:9]
	s_mov_b64 s[46:47], s[42:43]
	v_cvt_pk_bf16_f32 v7, v8, v9
	v_pk_mul_f32 v[8:9], v[10:11], v[22:23]
	s_nop 0
	v_pk_mul_f32 v[2:3], v[8:9], v[2:3]
	s_nop 0
	v_cvt_pk_bf16_f32 v8, v2, v3
	v_pk_mul_f32 v[2:3], v[12:13], v[24:25]
	s_nop 0
	v_pk_mul_f32 v[2:3], v[2:3], v[4:5]
	s_nop 0
	v_cvt_pk_bf16_f32 v9, v2, v3
	global_store_dwordx4 v[26:27], v[6:9], off
	s_cbranch_vccz .LBB0_657
	s_waitcnt vmcnt(0)
	s_cmpk_gt_u32 s18, 0xff
	s_cbranch_scc1 .LBB0_664
	s_barrier

.LBB0_696:
	s_add_u32 s44, s62, 0x100
	s_addc_u32 s45, s63, 0
	s_add_i32 s93, 0, 0x10000
	v_add_u32_e32 v58, s93, v197
	ds_read_b128 v[42:45], v58
	ds_read_b128 v[46:49], v58 offset:1024
	ds_read_b128 v[50:53], v58 offset:2048
	ds_read_b128 v[58:61], v58 offset:3072
	s_cmp_eq_u32 s92, 12
	s_cselect_b32 vcc_hi, s65, s45
	s_cselect_b32 vcc_lo, s88, s44
	s_cselect_b32 s97, s67, s91
	s_cselect_b32 s96, s89, s90
	v_lshl_add_u64 v[178:179], s[62:63], 0, v[208:209]
	s_add_i32 m0, s49, 0xc000
	ds_read_b128 v[62:65], v199
	ds_read_b128 v[66:69], v199 offset:1024
	ds_read_b128 v[78:81], v199 offset:2048
	ds_read_b128 v[82:85], v199 offset:3072
	ds_read_b128 v[162:165], v199 offset:4096
	ds_read_b128 v[166:169], v199 offset:5120
	ds_read_b128 v[170:173], v199 offset:6144
	ds_read_b128 v[174:177], v199 offset:7168
	global_load_lds_dwordx4 v[178:179], off
	v_lshl_add_u64 v[178:179], s[62:63], 0, v[206:207]
	s_add_i32 m0, s49, 0xe000
	s_nop 0
	global_load_lds_dwordx4 v[178:179], off
	s_waitcnt lgkmcnt(8)
	s_barrier
	s_waitcnt lgkmcnt(0)
	s_waitcnt lgkmcnt(0)
	v_mfma_f32_16x16x32_bf16 v[158:161], v[42:45], v[62:65], v[158:161]
	v_mfma_f32_16x16x32_bf16 v[154:157], v[50:53], v[62:65], v[154:157]
	v_mfma_f32_16x16x32_bf16 v[142:145], v[42:45], v[78:81], v[142:145]
	v_mfma_f32_16x16x32_bf16 v[138:141], v[50:53], v[78:81], v[138:141]
	v_mfma_f32_16x16x32_bf16 v[126:129], v[42:45], v[162:165], v[126:129]
	v_mfma_f32_16x16x32_bf16 v[122:125], v[50:53], v[162:165], v[122:125]
	v_mfma_f32_16x16x32_bf16 v[110:113], v[42:45], v[170:173], v[110:113]
	v_mfma_f32_16x16x32_bf16 v[106:109], v[50:53], v[170:173], v[106:109]
	v_mfma_f32_16x16x32_bf16 v[158:161], v[46:49], v[66:69], v[158:161]
	v_mfma_f32_16x16x32_bf16 v[154:157], v[58:61], v[66:69], v[154:157]
	v_mfma_f32_16x16x32_bf16 v[142:145], v[46:49], v[82:85], v[142:145]
	v_mfma_f32_16x16x32_bf16 v[138:141], v[58:61], v[82:85], v[138:141]
	v_mfma_f32_16x16x32_bf16 v[126:129], v[46:49], v[166:169], v[126:129]
	v_mfma_f32_16x16x32_bf16 v[122:125], v[58:61], v[166:169], v[122:125]
	v_mfma_f32_16x16x32_bf16 v[110:113], v[46:49], v[174:177], v[110:113]
	v_mfma_f32_16x16x32_bf16 v[106:109], v[58:61], v[174:177], v[106:109]
	s_barrier
	s_add_i32 s94, 0, 0x14000
	s_add_i32 s62, s93, s61
	v_add_u32_e32 v190, s94, v197
	v_lshl_add_u64 v[200:201], s[96:97], 0, v[0:1]
	s_mov_b32 m0, s62
	ds_read_b128 v[178:181], v190
	ds_read_b128 v[182:185], v190 offset:1024
	ds_read_b128 v[186:189], v190 offset:2048
	ds_read_b128 v[190:193], v190 offset:3072
	global_load_lds_dwordx4 v[200:201], off
	v_lshl_add_u64 v[202:203], s[96:97], 0, v[204:205]
	s_add_i32 m0, s62, 0x2000
	s_nop 0
	global_load_lds_dwordx4 v[202:203], off
	s_barrier
	s_waitcnt lgkmcnt(0)
	s_waitcnt lgkmcnt(0)
	v_mfma_f32_16x16x32_bf16 v[150:153], v[178:181], v[62:65], v[150:153]
	v_mfma_f32_16x16x32_bf16 v[62:65], v[186:189], v[62:65], v[146:149]
	v_mfma_f32_16x16x32_bf16 v[150:153], v[182:185], v[66:69], v[150:153]
	v_mfma_f32_16x16x32_bf16 v[62:65], v[190:193], v[66:69], v[62:65]
	v_mfma_f32_16x16x32_bf16 v[66:69], v[178:181], v[78:81], v[134:137]
	v_mfma_f32_16x16x32_bf16 v[78:81], v[186:189], v[78:81], v[130:133]
	v_mfma_f32_16x16x32_bf16 v[114:117], v[186:189], v[162:165], v[114:117]
	v_mfma_f32_16x16x32_bf16 v[102:105], v[178:181], v[170:173], v[102:105]
	v_mfma_f32_16x16x32_bf16 v[98:101], v[186:189], v[170:173], v[98:101]
	v_mfma_f32_16x16x32_bf16 v[66:69], v[182:185], v[82:85], v[66:69]
	v_mfma_f32_16x16x32_bf16 v[78:81], v[190:193], v[82:85], v[78:81]
	v_mfma_f32_16x16x32_bf16 v[82:85], v[178:181], v[162:165], v[118:121]
	v_mfma_f32_16x16x32_bf16 v[114:117], v[190:193], v[166:169], v[114:117]
	v_mfma_f32_16x16x32_bf16 v[102:105], v[182:185], v[174:177], v[102:105]
	v_mfma_f32_16x16x32_bf16 v[98:101], v[190:193], v[174:177], v[98:101]
	v_mfma_f32_16x16x32_bf16 v[82:85], v[182:185], v[166:169], v[82:85]
	s_mov_b32 m0, s49
	v_lshl_add_u64 v[218:219], vcc, 0, v[0:1]
	s_barrier
	ds_read_b128 v[118:121], v199 offset:16384
	ds_read_b128 v[130:133], v199 offset:17408
	ds_read_b128 v[134:137], v199 offset:18432
	ds_read_b128 v[146:149], v199 offset:19456
	ds_read_b128 v[162:165], v199 offset:20480
	ds_read_b128 v[166:169], v199 offset:21504
	ds_read_b128 v[170:173], v199 offset:22528
	ds_read_b128 v[174:177], v199 offset:23552
	global_load_lds_dwordx4 v[218:219], off
	v_lshl_add_u64 v[220:221], vcc, 0, v[204:205]
	s_mov_b32 m0, s55
	s_nop 0
	global_load_lds_dwordx4 v[220:221], off
	s_barrier
	s_waitcnt lgkmcnt(0)
	s_waitcnt lgkmcnt(0)
	v_mfma_f32_16x16x32_bf16 v[94:97], v[42:45], v[118:121], v[94:97]
	v_mfma_f32_16x16x32_bf16 v[90:93], v[50:53], v[118:121], v[90:93]
	v_mfma_f32_16x16x32_bf16 v[70:73], v[42:45], v[134:137], v[70:73]
	v_mfma_f32_16x16x32_bf16 v[54:57], v[50:53], v[134:137], v[54:57]
	v_mfma_f32_16x16x32_bf16 v[30:33], v[42:45], v[162:165], v[30:33]
	v_mfma_f32_16x16x32_bf16 v[26:29], v[50:53], v[162:165], v[26:29]
	v_mfma_f32_16x16x32_bf16 v[14:17], v[42:45], v[170:173], v[14:17]
	v_mfma_f32_16x16x32_bf16 v[10:13], v[50:53], v[170:173], v[10:13]
	v_mfma_f32_16x16x32_bf16 v[94:97], v[46:49], v[130:133], v[94:97]
	v_mfma_f32_16x16x32_bf16 v[90:93], v[58:61], v[130:133], v[90:93]
	v_mfma_f32_16x16x32_bf16 v[70:73], v[46:49], v[146:149], v[70:73]
	v_mfma_f32_16x16x32_bf16 v[54:57], v[58:61], v[146:149], v[54:57]
	v_mfma_f32_16x16x32_bf16 v[30:33], v[46:49], v[166:169], v[30:33]
	v_mfma_f32_16x16x32_bf16 v[26:29], v[58:61], v[166:169], v[26:29]
	v_mfma_f32_16x16x32_bf16 v[14:17], v[46:49], v[174:177], v[14:17]
	v_mfma_f32_16x16x32_bf16 v[10:13], v[58:61], v[174:177], v[10:13]
	s_barrier
	s_add_u32 s62, s96, 0x40000
	s_addc_u32 s63, s97, 0
	s_add_i32 s93, s94, s61
	v_lshl_add_u64 v[42:43], s[62:63], 0, v[0:1]
	s_mov_b32 m0, s93
	s_nop 0
	global_load_lds_dwordx4 v[42:43], off
	v_lshl_add_u64 v[42:43], s[62:63], 0, v[204:205]
	s_add_i32 m0, s93, 0x2000
	s_nop 0
	global_load_lds_dwordx4 v[42:43], off
	s_waitcnt vmcnt(6)
	s_barrier
	v_mfma_f32_16x16x32_bf16 v[38:41], v[178:181], v[134:137], v[38:41]
	v_mfma_f32_16x16x32_bf16 v[34:37], v[186:189], v[134:137], v[34:37]
	v_mfma_f32_16x16x32_bf16 v[22:25], v[178:181], v[162:165], v[22:25]
	v_mfma_f32_16x16x32_bf16 v[18:21], v[186:189], v[162:165], v[18:21]
	v_mfma_f32_16x16x32_bf16 v[6:9], v[178:181], v[170:173], v[6:9]
	v_mfma_f32_16x16x32_bf16 v[2:5], v[186:189], v[170:173], v[2:5]
	v_mfma_f32_16x16x32_bf16 v[42:45], v[178:181], v[118:121], v[86:89]
	v_mfma_f32_16x16x32_bf16 v[46:49], v[186:189], v[118:121], v[74:77]
	v_mfma_f32_16x16x32_bf16 v[38:41], v[182:185], v[146:149], v[38:41]
	v_mfma_f32_16x16x32_bf16 v[34:37], v[190:193], v[146:149], v[34:37]
	v_mfma_f32_16x16x32_bf16 v[22:25], v[182:185], v[166:169], v[22:25]
	v_mfma_f32_16x16x32_bf16 v[18:21], v[190:193], v[166:169], v[18:21]
	v_mfma_f32_16x16x32_bf16 v[6:9], v[182:185], v[174:177], v[6:9]
	v_mfma_f32_16x16x32_bf16 v[2:5], v[190:193], v[174:177], v[2:5]
	v_mfma_f32_16x16x32_bf16 v[42:45], v[182:185], v[130:133], v[42:45]
	v_mfma_f32_16x16x32_bf16 v[46:49], v[190:193], v[130:133], v[46:49]
	s_add_i32 s93, 0, 0x18000
	v_add_u32_e32 v86, s93, v197
	s_barrier
	ds_read_b128 v[50:53], v86
	ds_read_b128 v[58:61], v86 offset:1024
	ds_read_b128 v[74:77], v86 offset:2048
	ds_read_b128 v[86:89], v86 offset:3072
	s_add_u32 s62, vcc_lo, 0x40000
	s_addc_u32 s63, vcc_hi, 0
	s_mov_b32 m0, s81
	v_lshl_add_u64 v[134:135], s[62:63], 0, v[0:1]
	ds_read_b128 v[118:121], v199 offset:32768
	ds_read_b128 v[130:133], v199 offset:33792
	ds_read_b128 v[162:165], v199 offset:34816
	ds_read_b128 v[166:169], v199 offset:35840
	ds_read_b128 v[170:173], v199 offset:36864
	ds_read_b128 v[174:177], v199 offset:37888
	ds_read_b128 v[178:181], v199 offset:38912
	ds_read_b128 v[182:185], v199 offset:39936
	global_load_lds_dwordx4 v[134:135], off
	v_lshl_add_u64 v[134:135], s[62:63], 0, v[204:205]
	s_mov_b32 m0, s82
	s_nop 0
	global_load_lds_dwordx4 v[134:135], off
	s_waitcnt lgkmcnt(8)
	s_barrier
	s_waitcnt lgkmcnt(0)
	s_waitcnt lgkmcnt(0)
	v_mfma_f32_16x16x32_bf16 v[134:137], v[50:53], v[118:121], v[158:161]
	v_mfma_f32_16x16x32_bf16 v[158:161], v[58:61], v[130:133], v[134:137]
	v_mfma_f32_16x16x32_bf16 v[134:137], v[74:77], v[118:121], v[154:157]
	v_mfma_f32_16x16x32_bf16 v[154:157], v[86:89], v[130:133], v[134:137]
	v_mfma_f32_16x16x32_bf16 v[134:137], v[50:53], v[162:165], v[142:145]
	v_mfma_f32_16x16x32_bf16 v[142:145], v[58:61], v[166:169], v[134:137]
	v_mfma_f32_16x16x32_bf16 v[134:137], v[74:77], v[162:165], v[138:141]
	v_mfma_f32_16x16x32_bf16 v[126:129], v[50:53], v[170:173], v[126:129]
	v_mfma_f32_16x16x32_bf16 v[122:125], v[74:77], v[170:173], v[122:125]
	v_mfma_f32_16x16x32_bf16 v[110:113], v[50:53], v[178:181], v[110:113]
	v_mfma_f32_16x16x32_bf16 v[106:109], v[74:77], v[178:181], v[106:109]
	v_mfma_f32_16x16x32_bf16 v[138:141], v[86:89], v[166:169], v[134:137]
	v_mfma_f32_16x16x32_bf16 v[126:129], v[58:61], v[174:177], v[126:129]
	v_mfma_f32_16x16x32_bf16 v[122:125], v[86:89], v[174:177], v[122:125]
	v_mfma_f32_16x16x32_bf16 v[110:113], v[58:61], v[182:185], v[110:113]
	v_mfma_f32_16x16x32_bf16 v[106:109], v[86:89], v[182:185], v[106:109]
	s_barrier
	s_add_i32 s94, 0, 0x1c000
	v_add_u32_e32 v134, s94, v197
	s_add_i32 s62, s93, s61
	ds_read_b128 v[186:189], v134
	ds_read_b128 v[190:193], v134 offset:1024
	ds_read_b128 v[210:213], v134 offset:2048
	ds_read_b128 v[214:217], v134 offset:3072
	v_lshl_add_u64 v[134:135], v[200:201], 0, s[12:13]
	s_mov_b32 m0, s62
	s_nop 0
	global_load_lds_dwordx4 v[134:135], off
	v_lshl_add_u64 v[134:135], v[202:203], 0, s[12:13]
	s_add_i32 m0, s62, 0x2000
	s_nop 0
	global_load_lds_dwordx4 v[134:135], off
	s_barrier
	s_waitcnt lgkmcnt(0)
	s_waitcnt lgkmcnt(0)
	v_mfma_f32_16x16x32_bf16 v[62:65], v[210:213], v[118:121], v[62:65]
	v_mfma_f32_16x16x32_bf16 v[134:137], v[186:189], v[118:121], v[150:153]
	v_mfma_f32_16x16x32_bf16 v[146:149], v[214:217], v[130:133], v[62:65]
	v_mfma_f32_16x16x32_bf16 v[62:65], v[186:189], v[162:165], v[66:69]
	v_mfma_f32_16x16x32_bf16 v[150:153], v[190:193], v[130:133], v[134:137]
	v_mfma_f32_16x16x32_bf16 v[134:137], v[190:193], v[166:169], v[62:65]
	v_mfma_f32_16x16x32_bf16 v[62:65], v[210:213], v[162:165], v[78:81]
	v_mfma_f32_16x16x32_bf16 v[130:133], v[214:217], v[166:169], v[62:65]
	v_mfma_f32_16x16x32_bf16 v[62:65], v[186:189], v[170:173], v[82:85]
	v_mfma_f32_16x16x32_bf16 v[118:121], v[190:193], v[174:177], v[62:65]
	v_mfma_f32_16x16x32_bf16 v[62:65], v[210:213], v[170:173], v[114:117]
	v_mfma_f32_16x16x32_bf16 v[114:117], v[214:217], v[174:177], v[62:65]
	v_mfma_f32_16x16x32_bf16 v[62:65], v[186:189], v[178:181], v[102:105]
	v_mfma_f32_16x16x32_bf16 v[102:105], v[190:193], v[182:185], v[62:65]
	v_mfma_f32_16x16x32_bf16 v[62:65], v[210:213], v[178:181], v[98:101]
	v_mfma_f32_16x16x32_bf16 v[98:101], v[214:217], v[182:185], v[62:65]
	s_mov_b32 m0, s83
	v_lshl_add_u64 v[178:179], v[218:219], 0, s[12:13]
	s_barrier
	s_nop 2
	ds_read_b128 v[62:65], v199 offset:49152
	ds_read_b128 v[66:69], v199 offset:50176
	ds_read_b128 v[78:81], v199 offset:51200
	ds_read_b128 v[82:85], v199 offset:52224
	ds_read_b128 v[162:165], v199 offset:53248
	ds_read_b128 v[166:169], v199 offset:54272
	ds_read_b128 v[170:173], v199 offset:55296
	ds_read_b128 v[174:177], v199 offset:56320
	global_load_lds_dwordx4 v[178:179], off
	v_lshl_add_u64 v[178:179], v[220:221], 0, s[12:13]
	s_mov_b32 m0, s84
	s_nop 0
	global_load_lds_dwordx4 v[178:179], off
	s_barrier
	s_waitcnt lgkmcnt(0)
	s_waitcnt lgkmcnt(0)
	v_mfma_f32_16x16x32_bf16 v[94:97], v[50:53], v[62:65], v[94:97]
	v_mfma_f32_16x16x32_bf16 v[90:93], v[74:77], v[62:65], v[90:93]
	v_mfma_f32_16x16x32_bf16 v[70:73], v[50:53], v[78:81], v[70:73]
	v_mfma_f32_16x16x32_bf16 v[54:57], v[74:77], v[78:81], v[54:57]
	v_mfma_f32_16x16x32_bf16 v[30:33], v[50:53], v[162:165], v[30:33]
	v_mfma_f32_16x16x32_bf16 v[26:29], v[74:77], v[162:165], v[26:29]
	v_mfma_f32_16x16x32_bf16 v[14:17], v[50:53], v[170:173], v[14:17]
	v_mfma_f32_16x16x32_bf16 v[10:13], v[74:77], v[170:173], v[10:13]
	v_mfma_f32_16x16x32_bf16 v[94:97], v[58:61], v[66:69], v[94:97]
	v_mfma_f32_16x16x32_bf16 v[90:93], v[86:89], v[66:69], v[90:93]
	v_mfma_f32_16x16x32_bf16 v[70:73], v[58:61], v[82:85], v[70:73]
	v_mfma_f32_16x16x32_bf16 v[54:57], v[86:89], v[82:85], v[54:57]
	v_mfma_f32_16x16x32_bf16 v[30:33], v[58:61], v[166:169], v[30:33]
	v_mfma_f32_16x16x32_bf16 v[26:29], v[86:89], v[166:169], v[26:29]
	v_mfma_f32_16x16x32_bf16 v[14:17], v[58:61], v[174:177], v[14:17]
	v_mfma_f32_16x16x32_bf16 v[10:13], v[86:89], v[174:177], v[10:13]
	s_barrier
	s_add_u32 s62, s96, 0x40080
	s_addc_u32 s63, s97, 0
	s_add_i32 s93, s94, s61
	v_lshl_add_u64 v[50:51], s[62:63], 0, v[0:1]
	s_mov_b32 m0, s93
	s_nop 0
	global_load_lds_dwordx4 v[50:51], off
	v_lshl_add_u64 v[50:51], s[62:63], 0, v[204:205]
	s_add_i32 m0, s93, 0x2000
	s_nop 0
	global_load_lds_dwordx4 v[50:51], off
	s_waitcnt vmcnt(6)
	s_barrier
	v_mfma_f32_16x16x32_bf16 v[42:45], v[186:189], v[62:65], v[42:45]
	v_mfma_f32_16x16x32_bf16 v[86:89], v[190:193], v[66:69], v[42:45]
	v_mfma_f32_16x16x32_bf16 v[42:45], v[210:213], v[62:65], v[46:49]
	v_mfma_f32_16x16x32_bf16 v[38:41], v[186:189], v[78:81], v[38:41]
	v_mfma_f32_16x16x32_bf16 v[34:37], v[210:213], v[78:81], v[34:37]
	v_mfma_f32_16x16x32_bf16 v[22:25], v[186:189], v[162:165], v[22:25]
	v_mfma_f32_16x16x32_bf16 v[18:21], v[210:213], v[162:165], v[18:21]
	v_mfma_f32_16x16x32_bf16 v[6:9], v[186:189], v[170:173], v[6:9]
	v_mfma_f32_16x16x32_bf16 v[2:5], v[210:213], v[170:173], v[2:5]
	v_mfma_f32_16x16x32_bf16 v[74:77], v[214:217], v[66:69], v[42:45]
	v_mfma_f32_16x16x32_bf16 v[38:41], v[190:193], v[82:85], v[38:41]
	v_mfma_f32_16x16x32_bf16 v[34:37], v[214:217], v[82:85], v[34:37]
	v_mfma_f32_16x16x32_bf16 v[22:25], v[190:193], v[166:169], v[22:25]
	v_mfma_f32_16x16x32_bf16 v[18:21], v[214:217], v[166:169], v[18:21]
	v_mfma_f32_16x16x32_bf16 v[6:9], v[190:193], v[174:177], v[6:9]
	v_mfma_f32_16x16x32_bf16 v[2:5], v[214:217], v[174:177], v[2:5]
	s_add_i32 s92, s92, 2
	s_add_u32 s90, s90, 0x100
	s_addc_u32 s91, s91, 0
	s_cmp_gt_u32 s92, 13
	s_mov_b64 s[62:63], s[44:45]
	s_barrier
	s_cbranch_scc0 .LBB0_696
	v_lshl_or_b32 v162, s48, 8, v198
	v_ashrrev_i32_e32 v163, 31, v162
	v_cndmask_b32_e64 v42, 0, 1, s[4:5]
	v_cmp_ne_u32_e64 s[44:45], 1, v42
	s_andn2_b64 vcc, exec, s[4:5]
	v_lshlrev_b64 v[210:211], 2, v[162:163]
	s_cbranch_vccnz .LBB0_699
	v_lshl_add_u64 v[42:43], s[16:17], 0, v[210:211]
	v_lshl_add_u64 v[46:47], s[46:47], 0, v[210:211]
	global_load_dwordx4 v[78:81], v[42:43], off
	global_load_dwordx4 v[62:65], v[42:43], off offset:64
	global_load_dwordx4 v[82:85], v[46:47], off
	global_load_dwordx4 v[66:69], v[46:47], off offset:64
	global_load_dwordx4 v[50:53], v[42:43], off offset:512
	s_nop 0
	global_load_dwordx4 v[42:45], v[42:43], off offset:576
	s_nop 0
	global_load_dwordx4 v[58:61], v[46:47], off offset:512
	s_nop 0
	global_load_dwordx4 v[46:49], v[46:47], off offset:576

.LBB0_1445:
	s_add_u32 s64, s50, 0xfffc0080
	s_addc_u32 s65, s51, -1
	s_add_i32 s70, 0, 0x10000
	v_add_u32_e32 v0, s70, v198
	ds_read_b128 v[66:69], v0
	ds_read_b128 v[70:73], v0 offset:1024
	ds_read_b128 v[74:77], v0 offset:2048
	ds_read_b128 v[78:81], v0 offset:3072
	s_cmp_eq_u32 s69, 12
	s_cselect_b32 s67, s5, s65
	s_cselect_b32 s66, s10, s64
	s_cselect_b32 s65, s17, s68
	s_cselect_b32 s64, s47, s49
	v_lshl_add_u64 v[130:131], s[50:51], 0, v[228:229]
	s_add_i32 m0, s85, 0xc000
	ds_read_b128 v[82:85], v199
	ds_read_b128 v[86:89], v199 offset:1024
	ds_read_b128 v[90:93], v199 offset:2048
	ds_read_b128 v[94:97], v199 offset:3072
	ds_read_b128 v[106:109], v199 offset:4096
	ds_read_b128 v[110:113], v199 offset:5120
	ds_read_b128 v[122:125], v199 offset:6144
	ds_read_b128 v[126:129], v199 offset:7168
	global_load_lds_dwordx4 v[130:131], off
	v_lshl_add_u64 v[130:131], s[50:51], 0, v[226:227]
	s_add_i32 m0, s85, 0xe000
	s_nop 0
	global_load_lds_dwordx4 v[130:131], off
	s_waitcnt lgkmcnt(8)
	s_barrier
	s_waitcnt lgkmcnt(0)
	s_waitcnt lgkmcnt(0)
	v_mfma_f32_16x16x32_bf16 v[174:177], v[66:69], v[106:109], v[174:177]
	v_mfma_f32_16x16x32_bf16 v[170:173], v[74:77], v[106:109], v[170:173]
	v_mfma_f32_16x16x32_bf16 v[166:169], v[66:69], v[122:125], v[166:169]
	v_mfma_f32_16x16x32_bf16 v[162:165], v[74:77], v[122:125], v[162:165]
	v_mfma_f32_16x16x32_bf16 v[130:133], v[66:69], v[82:85], v[190:193]
	v_mfma_f32_16x16x32_bf16 v[134:137], v[74:77], v[82:85], v[186:189]
	v_mfma_f32_16x16x32_bf16 v[146:149], v[66:69], v[90:93], v[182:185]
	v_mfma_f32_16x16x32_bf16 v[150:153], v[74:77], v[90:93], v[178:181]
	v_mfma_f32_16x16x32_bf16 v[174:177], v[70:73], v[110:113], v[174:177]
	v_mfma_f32_16x16x32_bf16 v[170:173], v[78:81], v[110:113], v[170:173]
	v_mfma_f32_16x16x32_bf16 v[166:169], v[70:73], v[126:129], v[166:169]
	v_mfma_f32_16x16x32_bf16 v[162:165], v[78:81], v[126:129], v[162:165]
	v_mfma_f32_16x16x32_bf16 v[130:133], v[70:73], v[86:89], v[130:133]
	v_mfma_f32_16x16x32_bf16 v[134:137], v[78:81], v[86:89], v[134:137]
	v_mfma_f32_16x16x32_bf16 v[146:149], v[70:73], v[94:97], v[146:149]
	v_mfma_f32_16x16x32_bf16 v[150:153], v[78:81], v[94:97], v[150:153]
	s_barrier
	s_add_i32 vcc_lo, 0, 0x14000
	s_add_i32 s70, s70, s84
	v_add_u32_e32 v0, vcc_lo, v198
	v_lshl_add_u64 v[200:201], s[64:65], 0, v[206:207]
	s_mov_b32 m0, s70
	ds_read_b128 v[178:181], v0
	ds_read_b128 v[182:185], v0 offset:1024
	ds_read_b128 v[186:189], v0 offset:2048
	ds_read_b128 v[190:193], v0 offset:3072
	global_load_lds_dwordx4 v[200:201], off
	v_lshl_add_u64 v[202:203], s[64:65], 0, v[210:211]
	s_add_i32 m0, s70, 0x2000
	s_nop 0
	global_load_lds_dwordx4 v[202:203], off
	s_barrier
	s_waitcnt lgkmcnt(0)
	s_waitcnt lgkmcnt(0)
	v_mfma_f32_16x16x32_bf16 v[62:65], v[178:181], v[82:85], v[62:65]
	v_mfma_f32_16x16x32_bf16 v[58:61], v[186:189], v[82:85], v[58:61]
	v_mfma_f32_16x16x32_bf16 v[54:57], v[178:181], v[90:93], v[54:57]
	v_mfma_f32_16x16x32_bf16 v[50:53], v[186:189], v[90:93], v[50:53]
	v_mfma_f32_16x16x32_bf16 v[46:49], v[178:181], v[106:109], v[46:49]
	v_mfma_f32_16x16x32_bf16 v[42:45], v[186:189], v[106:109], v[42:45]
	v_mfma_f32_16x16x32_bf16 v[38:41], v[178:181], v[122:125], v[38:41]
	v_mfma_f32_16x16x32_bf16 v[34:37], v[186:189], v[122:125], v[34:37]
	v_mfma_f32_16x16x32_bf16 v[62:65], v[182:185], v[86:89], v[62:65]
	v_mfma_f32_16x16x32_bf16 v[58:61], v[190:193], v[86:89], v[58:61]
	v_mfma_f32_16x16x32_bf16 v[54:57], v[182:185], v[94:97], v[54:57]
	v_mfma_f32_16x16x32_bf16 v[50:53], v[190:193], v[94:97], v[50:53]
	v_mfma_f32_16x16x32_bf16 v[46:49], v[182:185], v[110:113], v[46:49]
	v_mfma_f32_16x16x32_bf16 v[42:45], v[190:193], v[110:113], v[42:45]
	v_mfma_f32_16x16x32_bf16 v[38:41], v[182:185], v[126:129], v[38:41]
	v_mfma_f32_16x16x32_bf16 v[34:37], v[190:193], v[126:129], v[34:37]
	s_mov_b32 m0, s85
	v_lshl_add_u64 v[248:249], s[66:67], 0, v[204:205]
	s_barrier
	ds_read_b128 v[82:85], v199 offset:16384
	ds_read_b128 v[86:89], v199 offset:17408
	ds_read_b128 v[90:93], v199 offset:18432
	ds_read_b128 v[94:97], v199 offset:19456
	ds_read_b128 v[106:109], v199 offset:20480
	ds_read_b128 v[110:113], v199 offset:21504
	ds_read_b128 v[122:125], v199 offset:22528
	ds_read_b128 v[126:129], v199 offset:23552
	global_load_lds_dwordx4 v[248:249], off
	v_lshl_add_u64 v[250:251], s[66:67], 0, v[208:209]
	s_mov_b32 m0, s86
	s_nop 0
	global_load_lds_dwordx4 v[250:251], off
	s_barrier
	s_waitcnt lgkmcnt(0)
	s_waitcnt lgkmcnt(0)
	v_mfma_f32_16x16x32_bf16 v[158:161], v[66:69], v[82:85], v[158:161]
	v_mfma_f32_16x16x32_bf16 v[154:157], v[74:77], v[82:85], v[154:157]
	v_mfma_f32_16x16x32_bf16 v[142:145], v[66:69], v[90:93], v[142:145]
	v_mfma_f32_16x16x32_bf16 v[138:141], v[74:77], v[90:93], v[138:141]
	v_mfma_f32_16x16x32_bf16 v[118:121], v[66:69], v[106:109], v[118:121]
	v_mfma_f32_16x16x32_bf16 v[114:117], v[74:77], v[106:109], v[114:117]
	v_mfma_f32_16x16x32_bf16 v[66:69], v[66:69], v[122:125], v[102:105]
	v_mfma_f32_16x16x32_bf16 v[158:161], v[70:73], v[86:89], v[158:161]
	v_mfma_f32_16x16x32_bf16 v[154:157], v[78:81], v[86:89], v[154:157]
	v_mfma_f32_16x16x32_bf16 v[142:145], v[70:73], v[94:97], v[142:145]
	v_mfma_f32_16x16x32_bf16 v[138:141], v[78:81], v[94:97], v[138:141]
	v_mfma_f32_16x16x32_bf16 v[118:121], v[70:73], v[110:113], v[118:121]
	v_mfma_f32_16x16x32_bf16 v[114:117], v[78:81], v[110:113], v[114:117]
	v_mfma_f32_16x16x32_bf16 v[66:69], v[70:73], v[126:129], v[66:69]
	v_mfma_f32_16x16x32_bf16 v[70:73], v[74:77], v[122:125], v[98:101]
	v_mfma_f32_16x16x32_bf16 v[70:73], v[78:81], v[126:129], v[70:73]
	s_barrier
	s_add_u32 s70, s64, 0x40000
	s_addc_u32 s71, s65, 0
	s_add_i32 vcc_lo, vcc_lo, s84
	v_lshl_add_u64 v[74:75], s[70:71], 0, v[206:207]
	s_mov_b32 m0, vcc_lo
	s_nop 0
	global_load_lds_dwordx4 v[74:75], off
	v_lshl_add_u64 v[74:75], s[70:71], 0, v[210:211]
	s_add_i32 m0, vcc_lo, 0x2000
	s_nop 0
	global_load_lds_dwordx4 v[74:75], off
	s_waitcnt vmcnt(6)
	s_barrier
	v_mfma_f32_16x16x32_bf16 v[30:33], v[178:181], v[82:85], v[30:33]
	v_mfma_f32_16x16x32_bf16 v[26:29], v[186:189], v[82:85], v[26:29]
	v_mfma_f32_16x16x32_bf16 v[22:25], v[178:181], v[90:93], v[22:25]
	v_mfma_f32_16x16x32_bf16 v[18:21], v[186:189], v[90:93], v[18:21]
	v_mfma_f32_16x16x32_bf16 v[14:17], v[178:181], v[106:109], v[14:17]
	v_mfma_f32_16x16x32_bf16 v[10:13], v[186:189], v[106:109], v[10:13]
	v_mfma_f32_16x16x32_bf16 v[6:9], v[178:181], v[122:125], v[6:9]
	v_mfma_f32_16x16x32_bf16 v[2:5], v[186:189], v[122:125], v[2:5]
	v_mfma_f32_16x16x32_bf16 v[30:33], v[182:185], v[86:89], v[30:33]
	v_mfma_f32_16x16x32_bf16 v[26:29], v[190:193], v[86:89], v[26:29]
	v_mfma_f32_16x16x32_bf16 v[22:25], v[182:185], v[94:97], v[22:25]
	v_mfma_f32_16x16x32_bf16 v[18:21], v[190:193], v[94:97], v[18:21]
	v_mfma_f32_16x16x32_bf16 v[14:17], v[182:185], v[110:113], v[14:17]
	v_mfma_f32_16x16x32_bf16 v[10:13], v[190:193], v[110:113], v[10:13]
	v_mfma_f32_16x16x32_bf16 v[6:9], v[182:185], v[126:129], v[6:9]
	v_mfma_f32_16x16x32_bf16 v[2:5], v[190:193], v[126:129], v[2:5]
	s_add_i32 s70, 0, 0x18000
	v_add_u32_e32 v0, s70, v198
	s_barrier
	ds_read_b128 v[74:77], v0
	ds_read_b128 v[78:81], v0 offset:1024
	ds_read_b128 v[82:85], v0 offset:2048
	ds_read_b128 v[86:89], v0 offset:3072
	s_add_u32 s66, s66, 0x40000
	s_addc_u32 s67, s67, 0
	s_mov_b32 m0, s87
	v_lshl_add_u64 v[178:179], s[66:67], 0, v[204:205]
	ds_read_b128 v[90:93], v199 offset:32768
	ds_read_b128 v[94:97], v199 offset:33792
	ds_read_b128 v[98:101], v199 offset:34816
	ds_read_b128 v[102:105], v199 offset:35840
	ds_read_b128 v[106:109], v199 offset:36864
	ds_read_b128 v[110:113], v199 offset:37888
	ds_read_b128 v[122:125], v199 offset:38912
	ds_read_b128 v[126:129], v199 offset:39936
	global_load_lds_dwordx4 v[178:179], off
	v_lshl_add_u64 v[178:179], s[66:67], 0, v[208:209]
	s_mov_b32 m0, s88
	s_nop 0
	global_load_lds_dwordx4 v[178:179], off
	s_waitcnt lgkmcnt(8)
	s_barrier
	s_waitcnt lgkmcnt(0)
	s_waitcnt lgkmcnt(0)
	v_mfma_f32_16x16x32_bf16 v[130:133], v[74:77], v[90:93], v[130:133]
	v_mfma_f32_16x16x32_bf16 v[190:193], v[78:81], v[94:97], v[130:133]
	v_mfma_f32_16x16x32_bf16 v[130:133], v[82:85], v[90:93], v[134:137]
	v_mfma_f32_16x16x32_bf16 v[186:189], v[86:89], v[94:97], v[130:133]
	v_mfma_f32_16x16x32_bf16 v[130:133], v[74:77], v[98:101], v[146:149]
	v_mfma_f32_16x16x32_bf16 v[182:185], v[78:81], v[102:105], v[130:133]
	v_mfma_f32_16x16x32_bf16 v[130:133], v[82:85], v[98:101], v[150:153]
	v_mfma_f32_16x16x32_bf16 v[178:181], v[86:89], v[102:105], v[130:133]
	v_mfma_f32_16x16x32_bf16 v[130:133], v[74:77], v[106:109], v[174:177]
	v_mfma_f32_16x16x32_bf16 v[174:177], v[78:81], v[110:113], v[130:133]
	v_mfma_f32_16x16x32_bf16 v[130:133], v[82:85], v[106:109], v[170:173]
	v_mfma_f32_16x16x32_bf16 v[170:173], v[86:89], v[110:113], v[130:133]
	v_mfma_f32_16x16x32_bf16 v[130:133], v[74:77], v[122:125], v[166:169]
	v_mfma_f32_16x16x32_bf16 v[166:169], v[78:81], v[126:129], v[130:133]
	v_mfma_f32_16x16x32_bf16 v[130:133], v[82:85], v[122:125], v[162:165]
	v_mfma_f32_16x16x32_bf16 v[162:165], v[86:89], v[126:129], v[130:133]
	s_barrier
	s_add_i32 s66, 0, 0x1c000
	s_add_i32 s67, s70, s84
	v_add_u32_e32 v0, s66, v198
	v_lshl_add_u64 v[200:201], v[200:201], 0, s[12:13]
	s_mov_b32 m0, s67
	ds_read_b128 v[130:133], v0
	ds_read_b128 v[134:137], v0 offset:1024
	ds_read_b128 v[146:149], v0 offset:2048
	ds_read_b128 v[150:153], v0 offset:3072
	global_load_lds_dwordx4 v[200:201], off
	v_lshl_add_u64 v[200:201], v[202:203], 0, s[12:13]
	s_add_i32 m0, s67, 0x2000
	s_nop 0
	global_load_lds_dwordx4 v[200:201], off
	s_barrier
	s_waitcnt lgkmcnt(0)
	s_waitcnt lgkmcnt(0)
	v_mfma_f32_16x16x32_bf16 v[62:65], v[130:133], v[90:93], v[62:65]
	v_mfma_f32_16x16x32_bf16 v[58:61], v[146:149], v[90:93], v[58:61]
	v_mfma_f32_16x16x32_bf16 v[54:57], v[130:133], v[98:101], v[54:57]
	v_mfma_f32_16x16x32_bf16 v[50:53], v[146:149], v[98:101], v[50:53]
	v_mfma_f32_16x16x32_bf16 v[46:49], v[130:133], v[106:109], v[46:49]
	v_mfma_f32_16x16x32_bf16 v[42:45], v[146:149], v[106:109], v[42:45]
	v_mfma_f32_16x16x32_bf16 v[38:41], v[130:133], v[122:125], v[38:41]
	v_mfma_f32_16x16x32_bf16 v[34:37], v[146:149], v[122:125], v[34:37]
	v_mfma_f32_16x16x32_bf16 v[62:65], v[134:137], v[94:97], v[62:65]
	v_mfma_f32_16x16x32_bf16 v[58:61], v[150:153], v[94:97], v[58:61]
	v_mfma_f32_16x16x32_bf16 v[54:57], v[134:137], v[102:105], v[54:57]
	v_mfma_f32_16x16x32_bf16 v[50:53], v[150:153], v[102:105], v[50:53]
	v_mfma_f32_16x16x32_bf16 v[46:49], v[134:137], v[110:113], v[46:49]
	v_mfma_f32_16x16x32_bf16 v[42:45], v[150:153], v[110:113], v[42:45]
	v_mfma_f32_16x16x32_bf16 v[38:41], v[134:137], v[126:129], v[38:41]
	v_mfma_f32_16x16x32_bf16 v[34:37], v[150:153], v[126:129], v[34:37]
	s_mov_b32 m0, s91
	v_lshl_add_u64 v[98:99], v[248:249], 0, s[12:13]
	s_barrier
	ds_read_b128 v[90:93], v199 offset:49152
	ds_read_b128 v[94:97], v199 offset:50176
	ds_read_b128 v[106:109], v199 offset:51200
	ds_read_b128 v[110:113], v199 offset:52224
	ds_read_b128 v[122:125], v199 offset:53248
	ds_read_b128 v[126:129], v199 offset:54272
	ds_read_b128 v[230:233], v199 offset:55296
	ds_read_b128 v[234:237], v199 offset:56320
	global_load_lds_dwordx4 v[98:99], off
	v_lshl_add_u64 v[98:99], v[250:251], 0, s[12:13]
	s_mov_b32 m0, s92
	s_nop 0
	global_load_lds_dwordx4 v[98:99], off
	s_barrier
	s_waitcnt lgkmcnt(0)
	s_waitcnt lgkmcnt(0)
	v_mfma_f32_16x16x32_bf16 v[98:101], v[74:77], v[90:93], v[158:161]
	v_mfma_f32_16x16x32_bf16 v[158:161], v[78:81], v[94:97], v[98:101]
	v_mfma_f32_16x16x32_bf16 v[98:101], v[82:85], v[90:93], v[154:157]
	v_mfma_f32_16x16x32_bf16 v[154:157], v[86:89], v[94:97], v[98:101]
	v_mfma_f32_16x16x32_bf16 v[98:101], v[74:77], v[106:109], v[142:145]
	v_mfma_f32_16x16x32_bf16 v[142:145], v[78:81], v[110:113], v[98:101]
	v_mfma_f32_16x16x32_bf16 v[98:101], v[82:85], v[106:109], v[138:141]
	v_mfma_f32_16x16x32_bf16 v[138:141], v[86:89], v[110:113], v[98:101]
	v_mfma_f32_16x16x32_bf16 v[98:101], v[74:77], v[122:125], v[118:121]
	v_mfma_f32_16x16x32_bf16 v[66:69], v[74:77], v[230:233], v[66:69]
	v_mfma_f32_16x16x32_bf16 v[118:121], v[78:81], v[126:129], v[98:101]
	v_mfma_f32_16x16x32_bf16 v[98:101], v[82:85], v[122:125], v[114:117]
	v_mfma_f32_16x16x32_bf16 v[102:105], v[78:81], v[234:237], v[66:69]
	v_mfma_f32_16x16x32_bf16 v[66:69], v[82:85], v[230:233], v[70:73]
	v_mfma_f32_16x16x32_bf16 v[114:117], v[86:89], v[126:129], v[98:101]
	v_mfma_f32_16x16x32_bf16 v[98:101], v[86:89], v[234:237], v[66:69]
	s_barrier
	s_add_u32 s64, s64, 0x40080
	s_addc_u32 s65, s65, 0
	s_add_i32 s66, s66, s84
	s_nop 0
	v_lshl_add_u64 v[66:67], s[64:65], 0, v[206:207]
	s_mov_b32 m0, s66
	s_nop 0
	global_load_lds_dwordx4 v[66:67], off
	v_lshl_add_u64 v[66:67], s[64:65], 0, v[210:211]
	s_add_i32 m0, s66, 0x2000
	s_nop 0
	global_load_lds_dwordx4 v[66:67], off
	s_waitcnt vmcnt(6)
	s_barrier
	v_mfma_f32_16x16x32_bf16 v[30:33], v[130:133], v[90:93], v[30:33]
	v_mfma_f32_16x16x32_bf16 v[26:29], v[146:149], v[90:93], v[26:29]
	v_mfma_f32_16x16x32_bf16 v[22:25], v[130:133], v[106:109], v[22:25]
	v_mfma_f32_16x16x32_bf16 v[18:21], v[146:149], v[106:109], v[18:21]
	v_mfma_f32_16x16x32_bf16 v[14:17], v[130:133], v[122:125], v[14:17]
	v_mfma_f32_16x16x32_bf16 v[10:13], v[146:149], v[122:125], v[10:13]
	v_mfma_f32_16x16x32_bf16 v[6:9], v[130:133], v[230:233], v[6:9]
	v_mfma_f32_16x16x32_bf16 v[2:5], v[146:149], v[230:233], v[2:5]
	v_mfma_f32_16x16x32_bf16 v[30:33], v[134:137], v[94:97], v[30:33]
	v_mfma_f32_16x16x32_bf16 v[26:29], v[150:153], v[94:97], v[26:29]
	v_mfma_f32_16x16x32_bf16 v[22:25], v[134:137], v[110:113], v[22:25]
	v_mfma_f32_16x16x32_bf16 v[18:21], v[150:153], v[110:113], v[18:21]
	v_mfma_f32_16x16x32_bf16 v[14:17], v[134:137], v[126:129], v[14:17]
	v_mfma_f32_16x16x32_bf16 v[10:13], v[150:153], v[126:129], v[10:13]
	v_mfma_f32_16x16x32_bf16 v[6:9], v[134:137], v[234:237], v[6:9]
	v_mfma_f32_16x16x32_bf16 v[2:5], v[150:153], v[234:237], v[2:5]
	s_add_i32 s69, s69, 2
	s_add_u32 s49, s49, 0x100
	s_addc_u32 s68, s68, 0
	s_add_u32 s50, s50, 0x100
	s_addc_u32 s51, s51, 0
	s_cmp_gt_u32 s69, 13
	s_barrier
	s_cbranch_scc0 .LBB0_1445
	s_lshl_b32 s17, s46, 8
	s_lshl_b32 s5, s48, 8
	s_add_i32 s5, s5, s89
	s_or_b32 s10, s17, s90
	v_or_b32_e32 v230, s5, v194
	s_cmpk_gt_i32 s10, 0x8ff
	s_mov_b64 s[46:47], -1
	s_cbranch_scc0 .LBB0_1454
	s_cmpk_gt_u32 s10, 0x93f
	s_cbranch_scc0 .LBB0_1451
	s_cmpk_lt_u32 s10, 0x960
	s_cselect_b64 s[46:47], -1, 0
	s_and_b64 s[48:49], s[40:41], s[46:47]
	s_and_saveexec_b64 s[46:47], s[48:49]
	s_cbranch_execz .LBB0_1450
	v_ashrrev_i32_e32 v231, 31, v230
	v_lshlrev_b64 v[66:67], 5, v[230:231]
	v_lshl_add_u64 v[70:71], s[8:9], 0, v[66:67]
	v_pk_mul_f32 v[68:69], v[192:193], s[38:39] op_sel_hi:[1,0]
	v_pk_mul_f32 v[66:67], v[190:191], s[38:39] op_sel_hi:[1,0]
	global_store_dwordx4 v[70:71], v[66:69], off
	s_nop 1
	v_pk_mul_f32 v[68:69], v[188:189], s[38:39] op_sel_hi:[1,0]
	v_pk_mul_f32 v[66:67], v[186:187], s[38:39] op_sel_hi:[1,0]
	global_store_dwordx4 v[70:71], v[66:69], off offset:16
	s_nop 1
	v_or_b32_e32 v66, 16, v230
	v_ashrrev_i32_e32 v67, 31, v66
	v_lshlrev_b64 v[66:67], 5, v[66:67]
	v_lshl_add_u64 v[70:71], s[8:9], 0, v[66:67]
	v_pk_mul_f32 v[68:69], v[184:185], s[38:39] op_sel_hi:[1,0]
	v_pk_mul_f32 v[66:67], v[182:183], s[38:39] op_sel_hi:[1,0]
	global_store_dwordx4 v[70:71], v[66:69], off
	s_nop 1
	v_pk_mul_f32 v[68:69], v[180:181], s[38:39] op_sel_hi:[1,0]
	v_pk_mul_f32 v[66:67], v[178:179], s[38:39] op_sel_hi:[1,0]
	global_store_dwordx4 v[70:71], v[66:69], off offset:16
	s_nop 1
	v_or_b32_e32 v66, 32, v230
	v_ashrrev_i32_e32 v67, 31, v66
	v_lshlrev_b64 v[66:67], 5, v[66:67]
	v_lshl_add_u64 v[70:71], s[8:9], 0, v[66:67]
	v_pk_mul_f32 v[68:69], v[176:177], s[38:39] op_sel_hi:[1,0]
	v_pk_mul_f32 v[66:67], v[174:175], s[38:39] op_sel_hi:[1,0]
	global_store_dwordx4 v[70:71], v[66:69], off
	s_nop 1
	v_pk_mul_f32 v[68:69], v[172:173], s[38:39] op_sel_hi:[1,0]
	v_pk_mul_f32 v[66:67], v[170:171], s[38:39] op_sel_hi:[1,0]
	global_store_dwordx4 v[70:71], v[66:69], off offset:16
	s_nop 1
	v_or_b32_e32 v66, 48, v230
	v_ashrrev_i32_e32 v67, 31, v66
	v_lshlrev_b64 v[66:67], 5, v[66:67]
	v_lshl_add_u64 v[70:71], s[8:9], 0, v[66:67]
	v_pk_mul_f32 v[68:69], v[168:169], s[38:39] op_sel_hi:[1,0]
	v_pk_mul_f32 v[66:67], v[166:167], s[38:39] op_sel_hi:[1,0]
	global_store_dwordx4 v[70:71], v[66:69], off
	s_nop 1
	v_pk_mul_f32 v[68:69], v[164:165], s[38:39] op_sel_hi:[1,0]
	v_pk_mul_f32 v[66:67], v[162:163], s[38:39] op_sel_hi:[1,0]
	global_store_dwordx4 v[70:71], v[66:69], off offset:16
	s_nop 1
	v_add_u32_e32 v66, 0x80, v230
	v_ashrrev_i32_e32 v67, 31, v66
	v_lshlrev_b64 v[66:67], 5, v[66:67]
	v_lshl_add_u64 v[70:71], s[8:9], 0, v[66:67]
	v_pk_mul_f32 v[68:69], v[160:161], s[38:39] op_sel_hi:[1,0]
	v_pk_mul_f32 v[66:67], v[158:159], s[38:39] op_sel_hi:[1,0]
	global_store_dwordx4 v[70:71], v[66:69], off
	s_nop 1
	v_pk_mul_f32 v[68:69], v[156:157], s[38:39] op_sel_hi:[1,0]
	v_pk_mul_f32 v[66:67], v[154:155], s[38:39] op_sel_hi:[1,0]
	global_store_dwordx4 v[70:71], v[66:69], off offset:16
	s_nop 1
	v_add_u32_e32 v66, 0x90, v230
	v_ashrrev_i32_e32 v67, 31, v66
	v_lshlrev_b64 v[66:67], 5, v[66:67]
	v_lshl_add_u64 v[70:71], s[8:9], 0, v[66:67]
	v_pk_mul_f32 v[68:69], v[144:145], s[38:39] op_sel_hi:[1,0]
	v_pk_mul_f32 v[66:67], v[142:143], s[38:39] op_sel_hi:[1,0]
	global_store_dwordx4 v[70:71], v[66:69], off
	s_nop 1
	v_pk_mul_f32 v[68:69], v[140:141], s[38:39] op_sel_hi:[1,0]
	v_pk_mul_f32 v[66:67], v[138:139], s[38:39] op_sel_hi:[1,0]
	global_store_dwordx4 v[70:71], v[66:69], off offset:16
	s_nop 1
	v_add_u32_e32 v66, 0xa0, v230
	v_ashrrev_i32_e32 v67, 31, v66
	v_lshlrev_b64 v[66:67], 5, v[66:67]
	v_lshl_add_u64 v[70:71], s[8:9], 0, v[66:67]
	v_pk_mul_f32 v[68:69], v[120:121], s[38:39] op_sel_hi:[1,0]
	v_pk_mul_f32 v[66:67], v[118:119], s[38:39] op_sel_hi:[1,0]
	global_store_dwordx4 v[70:71], v[66:69], off
	s_nop 1
	v_pk_mul_f32 v[68:69], v[116:117], s[38:39] op_sel_hi:[1,0]
	v_pk_mul_f32 v[66:67], v[114:115], s[38:39] op_sel_hi:[1,0]
	global_store_dwordx4 v[70:71], v[66:69], off offset:16
	s_nop 1
	v_add_u32_e32 v66, 0xb0, v230
	v_ashrrev_i32_e32 v67, 31, v66
	v_lshlrev_b64 v[66:67], 5, v[66:67]
	v_lshl_add_u64 v[70:71], s[8:9], 0, v[66:67]
	v_pk_mul_f32 v[68:69], v[104:105], s[38:39] op_sel_hi:[1,0]
	v_pk_mul_f32 v[66:67], v[102:103], s[38:39] op_sel_hi:[1,0]
	global_store_dwordx4 v[70:71], v[66:69], off
	s_nop 1
	v_pk_mul_f32 v[68:69], v[100:101], s[38:39] op_sel_hi:[1,0]
	v_pk_mul_f32 v[66:67], v[98:99], s[38:39] op_sel_hi:[1,0]
	global_store_dwordx4 v[70:71], v[66:69], off offset:16

.LBB0_1699:
	s_add_u32 s48, s46, 0xfffc0080
	s_addc_u32 s49, s47, -1
	s_add_i32 s80, 0, 0x10000
	v_add_u32_e32 v0, s80, v158
	ds_read_b128 v[130:133], v0
	ds_read_b128 v[148:151], v0 offset:1024
	ds_read_b128 v[152:155], v0 offset:2048
	ds_read_b128 v[164:167], v0 offset:3072
	s_cmp_eq_u32 s79, 12
	s_cselect_b32 s51, s10, s49
	s_cselect_b32 s50, s15, s48
	s_cselect_b32 s49, s9, s71
	s_cselect_b32 s48, s43, s45
	v_lshl_add_u64 v[156:157], s[46:47], 0, v[146:147]
	s_add_i32 m0, s57, 0xc000
	ds_read_b128 v[168:171], v163
	ds_read_b128 v[172:175], v163 offset:1024
	ds_read_b128 v[176:179], v163 offset:2048
	ds_read_b128 v[180:183], v163 offset:3072
	ds_read_b128 v[184:187], v163 offset:4096
	ds_read_b128 v[188:191], v163 offset:5120
	ds_read_b128 v[196:199], v163 offset:6144
	ds_read_b128 v[220:223], v163 offset:7168
	global_load_lds_dwordx4 v[156:157], off
	v_lshl_add_u64 v[156:157], s[46:47], 0, v[144:145]
	s_add_i32 m0, s57, 0xe000
	s_nop 0
	global_load_lds_dwordx4 v[156:157], off
	s_waitcnt lgkmcnt(8)
	s_barrier
	s_waitcnt lgkmcnt(0)
	s_waitcnt lgkmcnt(0)
	v_mfma_f32_16x16x32_bf16 v[126:129], v[130:133], v[168:171], v[126:129]
	v_mfma_f32_16x16x32_bf16 v[122:125], v[152:155], v[168:171], v[122:125]
	v_mfma_f32_16x16x32_bf16 v[110:113], v[130:133], v[176:179], v[110:113]
	v_mfma_f32_16x16x32_bf16 v[106:109], v[152:155], v[176:179], v[106:109]
	v_mfma_f32_16x16x32_bf16 v[94:97], v[130:133], v[184:187], v[94:97]
	v_mfma_f32_16x16x32_bf16 v[90:93], v[152:155], v[184:187], v[90:93]
	v_mfma_f32_16x16x32_bf16 v[78:81], v[130:133], v[196:199], v[78:81]
	v_mfma_f32_16x16x32_bf16 v[74:77], v[152:155], v[196:199], v[74:77]
	v_mfma_f32_16x16x32_bf16 v[126:129], v[148:151], v[172:175], v[126:129]
	v_mfma_f32_16x16x32_bf16 v[122:125], v[164:167], v[172:175], v[122:125]
	v_mfma_f32_16x16x32_bf16 v[110:113], v[148:151], v[180:183], v[110:113]
	v_mfma_f32_16x16x32_bf16 v[106:109], v[164:167], v[180:183], v[106:109]
	v_mfma_f32_16x16x32_bf16 v[94:97], v[148:151], v[188:191], v[94:97]
	v_mfma_f32_16x16x32_bf16 v[90:93], v[164:167], v[188:191], v[90:93]
	v_mfma_f32_16x16x32_bf16 v[78:81], v[148:151], v[220:223], v[78:81]
	v_mfma_f32_16x16x32_bf16 v[74:77], v[164:167], v[220:223], v[74:77]
	s_barrier
	s_add_i32 s82, 0, 0x14000
	s_add_i32 s80, s80, s56
	v_add_u32_e32 v0, s82, v158
	v_lshl_add_u64 v[156:157], s[48:49], 0, v[206:207]
	s_mov_b32 m0, s80
	ds_read_b128 v[224:227], v0
	ds_read_b128 v[228:231], v0 offset:1024
	ds_read_b128 v[232:235], v0 offset:2048
	ds_read_b128 v[250:253], v0 offset:3072
	global_load_lds_dwordx4 v[156:157], off
	v_lshl_add_u64 v[192:193], s[48:49], 0, v[210:211]
	s_add_i32 m0, s80, 0x2000
	s_nop 0
	global_load_lds_dwordx4 v[192:193], off
	s_barrier
	s_waitcnt lgkmcnt(0)
	s_waitcnt lgkmcnt(0)
	v_mfma_f32_16x16x32_bf16 v[118:121], v[224:227], v[168:171], v[118:121]
	v_mfma_f32_16x16x32_bf16 v[114:117], v[232:235], v[168:171], v[114:117]
	v_mfma_f32_16x16x32_bf16 v[102:105], v[224:227], v[176:179], v[102:105]
	v_mfma_f32_16x16x32_bf16 v[98:101], v[232:235], v[176:179], v[98:101]
	v_mfma_f32_16x16x32_bf16 v[86:89], v[224:227], v[184:187], v[86:89]
	v_mfma_f32_16x16x32_bf16 v[82:85], v[232:235], v[184:187], v[82:85]
	v_mfma_f32_16x16x32_bf16 v[70:73], v[224:227], v[196:199], v[70:73]
	v_mfma_f32_16x16x32_bf16 v[66:69], v[232:235], v[196:199], v[66:69]
	v_mfma_f32_16x16x32_bf16 v[118:121], v[228:231], v[172:175], v[118:121]
	v_mfma_f32_16x16x32_bf16 v[114:117], v[250:253], v[172:175], v[114:117]
	v_mfma_f32_16x16x32_bf16 v[102:105], v[228:231], v[180:183], v[102:105]
	v_mfma_f32_16x16x32_bf16 v[98:101], v[250:253], v[180:183], v[98:101]
	v_mfma_f32_16x16x32_bf16 v[86:89], v[228:231], v[188:191], v[86:89]
	v_mfma_f32_16x16x32_bf16 v[82:85], v[250:253], v[188:191], v[82:85]
	v_mfma_f32_16x16x32_bf16 v[70:73], v[228:231], v[220:223], v[70:73]
	v_mfma_f32_16x16x32_bf16 v[66:69], v[250:253], v[220:223], v[66:69]
	s_mov_b32 m0, s57
	v_lshl_add_u64 v[200:201], s[50:51], 0, v[204:205]
	s_barrier
	ds_read_b128 v[168:171], v163 offset:16384
	ds_read_b128 v[172:175], v163 offset:17408
	ds_read_b128 v[176:179], v163 offset:18432
	ds_read_b128 v[180:183], v163 offset:19456
	ds_read_b128 v[184:187], v163 offset:20480
	ds_read_b128 v[188:191], v163 offset:21504
	ds_read_b128 v[196:199], v163 offset:22528
	ds_read_b128 v[220:223], v163 offset:23552
	global_load_lds_dwordx4 v[200:201], off
	v_lshl_add_u64 v[202:203], s[50:51], 0, v[208:209]
	s_mov_b32 m0, s61
	s_nop 0
	global_load_lds_dwordx4 v[202:203], off
	s_barrier
	s_waitcnt lgkmcnt(0)
	s_waitcnt lgkmcnt(0)
	v_mfma_f32_16x16x32_bf16 v[62:65], v[130:133], v[168:171], v[62:65]
	v_mfma_f32_16x16x32_bf16 v[58:61], v[152:155], v[168:171], v[58:61]
	v_mfma_f32_16x16x32_bf16 v[46:49], v[130:133], v[176:179], v[46:49]
	v_mfma_f32_16x16x32_bf16 v[42:45], v[152:155], v[176:179], v[42:45]
	v_mfma_f32_16x16x32_bf16 v[30:33], v[130:133], v[184:187], v[30:33]
	v_mfma_f32_16x16x32_bf16 v[26:29], v[152:155], v[184:187], v[26:29]
	v_mfma_f32_16x16x32_bf16 v[14:17], v[130:133], v[196:199], v[14:17]
	v_mfma_f32_16x16x32_bf16 v[10:13], v[152:155], v[196:199], v[10:13]
	v_mfma_f32_16x16x32_bf16 v[62:65], v[148:151], v[172:175], v[62:65]
	v_mfma_f32_16x16x32_bf16 v[58:61], v[164:167], v[172:175], v[58:61]
	v_mfma_f32_16x16x32_bf16 v[46:49], v[148:151], v[180:183], v[46:49]
	v_mfma_f32_16x16x32_bf16 v[42:45], v[164:167], v[180:183], v[42:45]
	v_mfma_f32_16x16x32_bf16 v[30:33], v[148:151], v[188:191], v[30:33]
	v_mfma_f32_16x16x32_bf16 v[26:29], v[164:167], v[188:191], v[26:29]
	v_mfma_f32_16x16x32_bf16 v[14:17], v[148:151], v[220:223], v[14:17]
	v_mfma_f32_16x16x32_bf16 v[10:13], v[164:167], v[220:223], v[10:13]
	s_barrier
	s_add_u32 s80, s48, 0x40000
	s_addc_u32 s81, s49, 0
	s_add_i32 s82, s82, s56
	v_lshl_add_u64 v[130:131], s[80:81], 0, v[206:207]
	s_mov_b32 m0, s82
	s_nop 0
	global_load_lds_dwordx4 v[130:131], off
	v_lshl_add_u64 v[130:131], s[80:81], 0, v[210:211]
	s_add_i32 m0, s82, 0x2000
	s_nop 0
	global_load_lds_dwordx4 v[130:131], off
	s_waitcnt vmcnt(6)
	s_barrier
	v_mfma_f32_16x16x32_bf16 v[54:57], v[224:227], v[168:171], v[54:57]
	v_mfma_f32_16x16x32_bf16 v[50:53], v[232:235], v[168:171], v[50:53]
	v_mfma_f32_16x16x32_bf16 v[38:41], v[224:227], v[176:179], v[38:41]
	v_mfma_f32_16x16x32_bf16 v[34:37], v[232:235], v[176:179], v[34:37]
	v_mfma_f32_16x16x32_bf16 v[22:25], v[224:227], v[184:187], v[22:25]
	v_mfma_f32_16x16x32_bf16 v[18:21], v[232:235], v[184:187], v[18:21]
	v_mfma_f32_16x16x32_bf16 v[6:9], v[224:227], v[196:199], v[6:9]
	v_mfma_f32_16x16x32_bf16 v[2:5], v[232:235], v[196:199], v[2:5]
	v_mfma_f32_16x16x32_bf16 v[54:57], v[228:231], v[172:175], v[54:57]
	v_mfma_f32_16x16x32_bf16 v[50:53], v[250:253], v[172:175], v[50:53]
	v_mfma_f32_16x16x32_bf16 v[38:41], v[228:231], v[180:183], v[38:41]
	v_mfma_f32_16x16x32_bf16 v[34:37], v[250:253], v[180:183], v[34:37]
	v_mfma_f32_16x16x32_bf16 v[22:25], v[228:231], v[188:191], v[22:25]
	v_mfma_f32_16x16x32_bf16 v[18:21], v[250:253], v[188:191], v[18:21]
	v_mfma_f32_16x16x32_bf16 v[6:9], v[228:231], v[220:223], v[6:9]
	v_mfma_f32_16x16x32_bf16 v[2:5], v[250:253], v[220:223], v[2:5]
	s_add_i32 s80, 0, 0x18000
	v_add_u32_e32 v0, s80, v158
	s_barrier
	ds_read_b128 v[130:133], v0
	ds_read_b128 v[148:151], v0 offset:1024
	ds_read_b128 v[152:155], v0 offset:2048
	ds_read_b128 v[164:167], v0 offset:3072
	s_add_u32 s50, s50, 0x40000
	s_addc_u32 s51, s51, 0
	s_mov_b32 m0, s62
	v_lshl_add_u64 v[216:217], s[50:51], 0, v[204:205]
	ds_read_b128 v[168:171], v163 offset:32768
	ds_read_b128 v[172:175], v163 offset:33792
	ds_read_b128 v[176:179], v163 offset:34816
	ds_read_b128 v[180:183], v163 offset:35840
	ds_read_b128 v[184:187], v163 offset:36864
	ds_read_b128 v[188:191], v163 offset:37888
	ds_read_b128 v[196:199], v163 offset:38912
	ds_read_b128 v[220:223], v163 offset:39936
	global_load_lds_dwordx4 v[216:217], off
	v_lshl_add_u64 v[216:217], s[50:51], 0, v[208:209]
	s_mov_b32 m0, s63
	s_nop 0
	global_load_lds_dwordx4 v[216:217], off
	s_waitcnt lgkmcnt(8)
	s_barrier
	s_waitcnt lgkmcnt(0)
	s_waitcnt lgkmcnt(0)
	v_mfma_f32_16x16x32_bf16 v[126:129], v[130:133], v[168:171], v[126:129]
	v_mfma_f32_16x16x32_bf16 v[122:125], v[152:155], v[168:171], v[122:125]
	v_mfma_f32_16x16x32_bf16 v[110:113], v[130:133], v[176:179], v[110:113]
	v_mfma_f32_16x16x32_bf16 v[106:109], v[152:155], v[176:179], v[106:109]
	v_mfma_f32_16x16x32_bf16 v[94:97], v[130:133], v[184:187], v[94:97]
	v_mfma_f32_16x16x32_bf16 v[90:93], v[152:155], v[184:187], v[90:93]
	v_mfma_f32_16x16x32_bf16 v[78:81], v[130:133], v[196:199], v[78:81]
	v_mfma_f32_16x16x32_bf16 v[74:77], v[152:155], v[196:199], v[74:77]
	v_mfma_f32_16x16x32_bf16 v[126:129], v[148:151], v[172:175], v[126:129]
	v_mfma_f32_16x16x32_bf16 v[122:125], v[164:167], v[172:175], v[122:125]
	v_mfma_f32_16x16x32_bf16 v[110:113], v[148:151], v[180:183], v[110:113]
	v_mfma_f32_16x16x32_bf16 v[106:109], v[164:167], v[180:183], v[106:109]
	v_mfma_f32_16x16x32_bf16 v[94:97], v[148:151], v[188:191], v[94:97]
	v_mfma_f32_16x16x32_bf16 v[90:93], v[164:167], v[188:191], v[90:93]
	v_mfma_f32_16x16x32_bf16 v[78:81], v[148:151], v[220:223], v[78:81]
	v_mfma_f32_16x16x32_bf16 v[74:77], v[164:167], v[220:223], v[74:77]
	s_barrier
	s_add_i32 s50, 0, 0x1c000
	s_add_i32 s51, s80, s56
	v_add_u32_e32 v0, s50, v158
	v_lshl_add_u64 v[156:157], v[156:157], 0, s[12:13]
	s_mov_b32 m0, s51
	ds_read_b128 v[224:227], v0
	ds_read_b128 v[228:231], v0 offset:1024
	ds_read_b128 v[232:235], v0 offset:2048
	ds_read_b128 v[250:253], v0 offset:3072
	global_load_lds_dwordx4 v[156:157], off
	v_lshl_add_u64 v[156:157], v[192:193], 0, s[12:13]
	s_add_i32 m0, s51, 0x2000
	s_nop 0
	global_load_lds_dwordx4 v[156:157], off
	s_barrier
	s_waitcnt lgkmcnt(0)
	s_waitcnt lgkmcnt(0)
	v_mfma_f32_16x16x32_bf16 v[118:121], v[224:227], v[168:171], v[118:121]
	v_mfma_f32_16x16x32_bf16 v[114:117], v[232:235], v[168:171], v[114:117]
	v_mfma_f32_16x16x32_bf16 v[102:105], v[224:227], v[176:179], v[102:105]
	v_mfma_f32_16x16x32_bf16 v[98:101], v[232:235], v[176:179], v[98:101]
	v_mfma_f32_16x16x32_bf16 v[86:89], v[224:227], v[184:187], v[86:89]
	v_mfma_f32_16x16x32_bf16 v[82:85], v[232:235], v[184:187], v[82:85]
	v_mfma_f32_16x16x32_bf16 v[70:73], v[224:227], v[196:199], v[70:73]
	v_mfma_f32_16x16x32_bf16 v[66:69], v[232:235], v[196:199], v[66:69]
	v_mfma_f32_16x16x32_bf16 v[118:121], v[228:231], v[172:175], v[118:121]
	v_mfma_f32_16x16x32_bf16 v[114:117], v[250:253], v[172:175], v[114:117]
	v_mfma_f32_16x16x32_bf16 v[102:105], v[228:231], v[180:183], v[102:105]
	v_mfma_f32_16x16x32_bf16 v[98:101], v[250:253], v[180:183], v[98:101]
	v_mfma_f32_16x16x32_bf16 v[86:89], v[228:231], v[188:191], v[86:89]
	v_mfma_f32_16x16x32_bf16 v[82:85], v[250:253], v[188:191], v[82:85]
	v_mfma_f32_16x16x32_bf16 v[70:73], v[228:231], v[220:223], v[70:73]
	v_mfma_f32_16x16x32_bf16 v[66:69], v[250:253], v[220:223], v[66:69]
	s_mov_b32 m0, s66
	v_lshl_add_u64 v[156:157], v[200:201], 0, s[12:13]
	s_barrier
	ds_read_b128 v[168:171], v163 offset:49152
	ds_read_b128 v[172:175], v163 offset:50176
	ds_read_b128 v[176:179], v163 offset:51200
	ds_read_b128 v[180:183], v163 offset:52224
	ds_read_b128 v[184:187], v163 offset:53248
	ds_read_b128 v[188:191], v163 offset:54272
	ds_read_b128 v[196:199], v163 offset:55296
	ds_read_b128 v[220:223], v163 offset:56320
	global_load_lds_dwordx4 v[156:157], off
	v_lshl_add_u64 v[156:157], v[202:203], 0, s[12:13]
	s_mov_b32 m0, s67
	s_nop 0
	global_load_lds_dwordx4 v[156:157], off
	s_barrier
	s_waitcnt lgkmcnt(0)
	s_waitcnt lgkmcnt(0)
	v_mfma_f32_16x16x32_bf16 v[62:65], v[130:133], v[168:171], v[62:65]
	v_mfma_f32_16x16x32_bf16 v[58:61], v[152:155], v[168:171], v[58:61]
	v_mfma_f32_16x16x32_bf16 v[46:49], v[130:133], v[176:179], v[46:49]
	v_mfma_f32_16x16x32_bf16 v[42:45], v[152:155], v[176:179], v[42:45]
	v_mfma_f32_16x16x32_bf16 v[30:33], v[130:133], v[184:187], v[30:33]
	v_mfma_f32_16x16x32_bf16 v[26:29], v[152:155], v[184:187], v[26:29]
	v_mfma_f32_16x16x32_bf16 v[14:17], v[130:133], v[196:199], v[14:17]
	v_mfma_f32_16x16x32_bf16 v[10:13], v[152:155], v[196:199], v[10:13]
	v_mfma_f32_16x16x32_bf16 v[62:65], v[148:151], v[172:175], v[62:65]
	v_mfma_f32_16x16x32_bf16 v[58:61], v[164:167], v[172:175], v[58:61]
	v_mfma_f32_16x16x32_bf16 v[46:49], v[148:151], v[180:183], v[46:49]
	v_mfma_f32_16x16x32_bf16 v[42:45], v[164:167], v[180:183], v[42:45]
	v_mfma_f32_16x16x32_bf16 v[30:33], v[148:151], v[188:191], v[30:33]
	v_mfma_f32_16x16x32_bf16 v[26:29], v[164:167], v[188:191], v[26:29]
	v_mfma_f32_16x16x32_bf16 v[14:17], v[148:151], v[220:223], v[14:17]
	v_mfma_f32_16x16x32_bf16 v[10:13], v[164:167], v[220:223], v[10:13]
	s_barrier
	s_add_u32 s48, s48, 0x40080
	s_addc_u32 s49, s49, 0
	s_add_i32 s50, s50, s56
	v_lshl_add_u64 v[130:131], s[48:49], 0, v[206:207]
	s_mov_b32 m0, s50
	s_nop 0
	global_load_lds_dwordx4 v[130:131], off
	v_lshl_add_u64 v[130:131], s[48:49], 0, v[210:211]
	s_add_i32 m0, s50, 0x2000
	s_nop 0
	global_load_lds_dwordx4 v[130:131], off
	s_waitcnt vmcnt(6)
	s_barrier
	v_mfma_f32_16x16x32_bf16 v[54:57], v[224:227], v[168:171], v[54:57]
	v_mfma_f32_16x16x32_bf16 v[50:53], v[232:235], v[168:171], v[50:53]
	v_mfma_f32_16x16x32_bf16 v[38:41], v[224:227], v[176:179], v[38:41]
	v_mfma_f32_16x16x32_bf16 v[34:37], v[232:235], v[176:179], v[34:37]
	v_mfma_f32_16x16x32_bf16 v[22:25], v[224:227], v[184:187], v[22:25]
	v_mfma_f32_16x16x32_bf16 v[18:21], v[232:235], v[184:187], v[18:21]
	v_mfma_f32_16x16x32_bf16 v[6:9], v[224:227], v[196:199], v[6:9]
	v_mfma_f32_16x16x32_bf16 v[2:5], v[232:235], v[196:199], v[2:5]
	v_mfma_f32_16x16x32_bf16 v[54:57], v[228:231], v[172:175], v[54:57]
	v_mfma_f32_16x16x32_bf16 v[50:53], v[250:253], v[172:175], v[50:53]
	v_mfma_f32_16x16x32_bf16 v[38:41], v[228:231], v[180:183], v[38:41]
	v_mfma_f32_16x16x32_bf16 v[34:37], v[250:253], v[180:183], v[34:37]
	v_mfma_f32_16x16x32_bf16 v[22:25], v[228:231], v[188:191], v[22:25]
	v_mfma_f32_16x16x32_bf16 v[18:21], v[250:253], v[188:191], v[18:21]
	v_mfma_f32_16x16x32_bf16 v[6:9], v[228:231], v[220:223], v[6:9]
	v_mfma_f32_16x16x32_bf16 v[2:5], v[250:253], v[220:223], v[2:5]
	s_add_i32 s79, s79, 2
	s_add_u32 s45, s45, 0x100
	s_addc_u32 s71, s71, 0
	s_add_u32 s46, s46, 0x100
	s_addc_u32 s47, s47, 0
	s_cmp_gt_u32 s79, 13
	s_barrier
	s_cbranch_scc0 .LBB0_1699
	s_lshl_b32 s51, s44, 8
	s_add_i32 s51, s51, s64
	s_ashr_i32 s49, s42, 4
	s_mul_i32 s71, s49, 12
	s_ashr_i32 s10, s51, 6
	s_lshl_b32 s48, s42, 8
	s_add_i32 s42, s10, s71
	s_ashr_i32 s43, s42, 31
	s_and_b32 s9, s48, 0xf00
	s_lshl_b64 s[44:45], s[42:43], 18
	v_cndmask_b32_e64 v0, 0, 1, s[26:27]
	s_or_b32 s15, s9, s65
	s_mov_b64 s[46:47], -1
	v_cmp_ne_u32_e64 s[42:43], 1, v0
	s_andn2_b64 vcc, exec, s[26:27]
	v_cvt_pk_bf16_f32 v130, v126, v127
	v_cvt_pk_bf16_f32 v131, v128, v129
	v_cvt_pk_bf16_f32 v132, v122, v123
	v_cvt_pk_bf16_f32 v133, v124, v125
	v_lshl_add_u64 v[154:155], s[44:45], 1, v[136:137]
	s_cbranch_vccnz .LBB0_1702
	s_lshl_b32 s10, s15, 7
	v_lshl_add_u64 v[148:149], v[154:155], 0, s[10:11]
	s_mov_b64 s[46:47], 0
	global_store_dwordx4 v[148:149], v[130:133], off

.LBB0_1786:
	s_add_u32 s42, s40, 0xfffc0080
	s_addc_u32 s43, s41, -1
	s_add_i32 s67, 0, 0x10000
	v_add_u32_e32 v0, s67, v131
	ds_read_b128 v[150:153], v0
	ds_read_b128 v[154:157], v0 offset:1024
	ds_read_b128 v[158:161], v0 offset:2048
	ds_read_b128 v[162:165], v0 offset:3072
	s_cmp_eq_u32 s66, 12
	s_cselect_b32 s45, s9, s43
	s_cselect_b32 s44, s10, s42
	s_cselect_b32 s43, s5, s59
	s_cselect_b32 s42, s27, s29
	v_lshl_add_u64 v[200:201], s[40:41], 0, v[148:149]
	s_add_i32 m0, s51, 0xc000
	ds_read_b128 v[166:169], v139
	ds_read_b128 v[170:173], v139 offset:1024
	ds_read_b128 v[174:177], v139 offset:2048
	ds_read_b128 v[178:181], v139 offset:3072
	ds_read_b128 v[182:185], v139 offset:4096
	ds_read_b128 v[186:189], v139 offset:5120
	ds_read_b128 v[190:193], v139 offset:6144
	ds_read_b128 v[196:199], v139 offset:7168
	global_load_lds_dwordx4 v[200:201], off
	v_lshl_add_u64 v[200:201], s[40:41], 0, v[146:147]
	s_add_i32 m0, s51, 0xe000
	s_nop 0
	global_load_lds_dwordx4 v[200:201], off
	s_waitcnt lgkmcnt(8)
	s_barrier
	s_waitcnt lgkmcnt(0)
	s_waitcnt lgkmcnt(0)
	v_mfma_f32_16x16x32_bf16 v[126:129], v[150:153], v[166:169], v[126:129]
	v_mfma_f32_16x16x32_bf16 v[122:125], v[158:161], v[166:169], v[122:125]
	v_mfma_f32_16x16x32_bf16 v[118:121], v[150:153], v[174:177], v[118:121]
	v_mfma_f32_16x16x32_bf16 v[114:117], v[158:161], v[174:177], v[114:117]
	v_mfma_f32_16x16x32_bf16 v[110:113], v[150:153], v[182:185], v[110:113]
	v_mfma_f32_16x16x32_bf16 v[106:109], v[158:161], v[182:185], v[106:109]
	v_mfma_f32_16x16x32_bf16 v[102:105], v[150:153], v[190:193], v[102:105]
	v_mfma_f32_16x16x32_bf16 v[98:101], v[158:161], v[190:193], v[98:101]
	v_mfma_f32_16x16x32_bf16 v[126:129], v[154:157], v[170:173], v[126:129]
	v_mfma_f32_16x16x32_bf16 v[122:125], v[162:165], v[170:173], v[122:125]
	v_mfma_f32_16x16x32_bf16 v[118:121], v[154:157], v[178:181], v[118:121]
	v_mfma_f32_16x16x32_bf16 v[114:117], v[162:165], v[178:181], v[114:117]
	v_mfma_f32_16x16x32_bf16 v[110:113], v[154:157], v[186:189], v[110:113]
	v_mfma_f32_16x16x32_bf16 v[106:109], v[162:165], v[186:189], v[106:109]
	v_mfma_f32_16x16x32_bf16 v[102:105], v[154:157], v[196:199], v[102:105]
	v_mfma_f32_16x16x32_bf16 v[98:101], v[162:165], v[196:199], v[98:101]
	s_barrier
	s_add_i32 s70, 0, 0x14000
	s_add_i32 s67, s67, s50
	v_add_u32_e32 v0, s70, v131
	v_lshl_add_u64 v[200:201], s[42:43], 0, v[206:207]
	s_mov_b32 m0, s67
	ds_read_b128 v[212:215], v0
	ds_read_b128 v[216:219], v0 offset:1024
	ds_read_b128 v[220:223], v0 offset:2048
	ds_read_b128 v[224:227], v0 offset:3072
	global_load_lds_dwordx4 v[200:201], off
	v_lshl_add_u64 v[202:203], s[42:43], 0, v[210:211]
	s_add_i32 m0, s67, 0x2000
	s_nop 0
	global_load_lds_dwordx4 v[202:203], off
	s_barrier
	s_waitcnt lgkmcnt(0)
	s_waitcnt lgkmcnt(0)
	v_mfma_f32_16x16x32_bf16 v[66:69], v[212:215], v[166:169], v[66:69]
	v_mfma_f32_16x16x32_bf16 v[58:61], v[220:223], v[166:169], v[58:61]
	v_mfma_f32_16x16x32_bf16 v[54:57], v[212:215], v[174:177], v[54:57]
	v_mfma_f32_16x16x32_bf16 v[50:53], v[220:223], v[174:177], v[50:53]
	v_mfma_f32_16x16x32_bf16 v[46:49], v[212:215], v[182:185], v[46:49]
	v_mfma_f32_16x16x32_bf16 v[42:45], v[220:223], v[182:185], v[42:45]
	v_mfma_f32_16x16x32_bf16 v[38:41], v[212:215], v[190:193], v[38:41]
	v_mfma_f32_16x16x32_bf16 v[34:37], v[220:223], v[190:193], v[34:37]
	v_mfma_f32_16x16x32_bf16 v[66:69], v[216:219], v[170:173], v[66:69]
	v_mfma_f32_16x16x32_bf16 v[58:61], v[224:227], v[170:173], v[58:61]
	v_mfma_f32_16x16x32_bf16 v[54:57], v[216:219], v[178:181], v[54:57]
	v_mfma_f32_16x16x32_bf16 v[50:53], v[224:227], v[178:181], v[50:53]
	v_mfma_f32_16x16x32_bf16 v[46:49], v[216:219], v[186:189], v[46:49]
	v_mfma_f32_16x16x32_bf16 v[42:45], v[224:227], v[186:189], v[42:45]
	v_mfma_f32_16x16x32_bf16 v[38:41], v[216:219], v[196:199], v[38:41]
	v_mfma_f32_16x16x32_bf16 v[34:37], v[224:227], v[196:199], v[34:37]
	s_mov_b32 m0, s51
	v_lshl_add_u64 v[228:229], s[44:45], 0, v[204:205]
	s_barrier
	ds_read_b128 v[166:169], v139 offset:16384
	ds_read_b128 v[170:173], v139 offset:17408
	ds_read_b128 v[174:177], v139 offset:18432
	ds_read_b128 v[178:181], v139 offset:19456
	ds_read_b128 v[182:185], v139 offset:20480
	ds_read_b128 v[186:189], v139 offset:21504
	ds_read_b128 v[190:193], v139 offset:22528
	ds_read_b128 v[196:199], v139 offset:23552
	global_load_lds_dwordx4 v[228:229], off
	v_lshl_add_u64 v[230:231], s[44:45], 0, v[208:209]
	s_mov_b32 m0, s52
	s_nop 0
	global_load_lds_dwordx4 v[230:231], off
	s_barrier
	s_waitcnt lgkmcnt(0)
	s_waitcnt lgkmcnt(0)
	v_mfma_f32_16x16x32_bf16 v[94:97], v[150:153], v[166:169], v[94:97]
	v_mfma_f32_16x16x32_bf16 v[90:93], v[158:161], v[166:169], v[90:93]
	v_mfma_f32_16x16x32_bf16 v[86:89], v[150:153], v[174:177], v[86:89]
	v_mfma_f32_16x16x32_bf16 v[82:85], v[158:161], v[174:177], v[82:85]
	v_mfma_f32_16x16x32_bf16 v[78:81], v[150:153], v[182:185], v[78:81]
	v_mfma_f32_16x16x32_bf16 v[74:77], v[158:161], v[182:185], v[74:77]
	v_mfma_f32_16x16x32_bf16 v[70:73], v[150:153], v[190:193], v[70:73]
	v_mfma_f32_16x16x32_bf16 v[62:65], v[158:161], v[190:193], v[62:65]
	v_mfma_f32_16x16x32_bf16 v[94:97], v[154:157], v[170:173], v[94:97]
	v_mfma_f32_16x16x32_bf16 v[90:93], v[162:165], v[170:173], v[90:93]
	v_mfma_f32_16x16x32_bf16 v[86:89], v[154:157], v[178:181], v[86:89]
	v_mfma_f32_16x16x32_bf16 v[82:85], v[162:165], v[178:181], v[82:85]
	v_mfma_f32_16x16x32_bf16 v[78:81], v[154:157], v[186:189], v[78:81]
	v_mfma_f32_16x16x32_bf16 v[74:77], v[162:165], v[186:189], v[74:77]
	v_mfma_f32_16x16x32_bf16 v[70:73], v[154:157], v[196:199], v[70:73]
	v_mfma_f32_16x16x32_bf16 v[62:65], v[162:165], v[196:199], v[62:65]
	s_barrier
	s_add_u32 s68, s42, 0x40000
	s_addc_u32 s69, s43, 0
	s_add_i32 s67, s70, s50
	v_lshl_add_u64 v[150:151], s[68:69], 0, v[206:207]
	s_mov_b32 m0, s67
	s_nop 0
	global_load_lds_dwordx4 v[150:151], off
	v_lshl_add_u64 v[150:151], s[68:69], 0, v[210:211]
	s_add_i32 m0, s67, 0x2000
	s_nop 0
	global_load_lds_dwordx4 v[150:151], off
	s_waitcnt vmcnt(6)
	s_barrier
	v_mfma_f32_16x16x32_bf16 v[30:33], v[212:215], v[166:169], v[30:33]
	v_mfma_f32_16x16x32_bf16 v[26:29], v[220:223], v[166:169], v[26:29]
	v_mfma_f32_16x16x32_bf16 v[22:25], v[212:215], v[174:177], v[22:25]
	v_mfma_f32_16x16x32_bf16 v[18:21], v[220:223], v[174:177], v[18:21]
	v_mfma_f32_16x16x32_bf16 v[14:17], v[212:215], v[182:185], v[14:17]
	v_mfma_f32_16x16x32_bf16 v[10:13], v[220:223], v[182:185], v[10:13]
	v_mfma_f32_16x16x32_bf16 v[6:9], v[212:215], v[190:193], v[6:9]
	v_mfma_f32_16x16x32_bf16 v[2:5], v[220:223], v[190:193], v[2:5]
	v_mfma_f32_16x16x32_bf16 v[30:33], v[216:219], v[170:173], v[30:33]
	v_mfma_f32_16x16x32_bf16 v[26:29], v[224:227], v[170:173], v[26:29]
	v_mfma_f32_16x16x32_bf16 v[22:25], v[216:219], v[178:181], v[22:25]
	v_mfma_f32_16x16x32_bf16 v[18:21], v[224:227], v[178:181], v[18:21]
	v_mfma_f32_16x16x32_bf16 v[14:17], v[216:219], v[186:189], v[14:17]
	v_mfma_f32_16x16x32_bf16 v[10:13], v[224:227], v[186:189], v[10:13]
	v_mfma_f32_16x16x32_bf16 v[6:9], v[216:219], v[196:199], v[6:9]
	v_mfma_f32_16x16x32_bf16 v[2:5], v[224:227], v[196:199], v[2:5]
	s_add_i32 s67, 0, 0x18000
	v_add_u32_e32 v0, s67, v131
	s_barrier
	ds_read_b128 v[150:153], v0
	ds_read_b128 v[154:157], v0 offset:1024
	ds_read_b128 v[158:161], v0 offset:2048
	ds_read_b128 v[162:165], v0 offset:3072
	s_add_u32 s44, s44, 0x40000
	s_addc_u32 s45, s45, 0
	s_mov_b32 m0, s53
	v_lshl_add_u64 v[212:213], s[44:45], 0, v[204:205]
	ds_read_b128 v[166:169], v139 offset:32768
	ds_read_b128 v[170:173], v139 offset:33792
	ds_read_b128 v[174:177], v139 offset:34816
	ds_read_b128 v[178:181], v139 offset:35840
	ds_read_b128 v[182:185], v139 offset:36864
	ds_read_b128 v[186:189], v139 offset:37888
	ds_read_b128 v[190:193], v139 offset:38912
	ds_read_b128 v[196:199], v139 offset:39936
	global_load_lds_dwordx4 v[212:213], off
	v_lshl_add_u64 v[212:213], s[44:45], 0, v[208:209]
	s_mov_b32 m0, s54
	s_nop 0
	global_load_lds_dwordx4 v[212:213], off
	s_waitcnt lgkmcnt(8)
	s_barrier
	s_waitcnt lgkmcnt(0)
	s_waitcnt lgkmcnt(0)
	v_mfma_f32_16x16x32_bf16 v[126:129], v[150:153], v[166:169], v[126:129]
	v_mfma_f32_16x16x32_bf16 v[122:125], v[158:161], v[166:169], v[122:125]
	v_mfma_f32_16x16x32_bf16 v[118:121], v[150:153], v[174:177], v[118:121]
	v_mfma_f32_16x16x32_bf16 v[114:117], v[158:161], v[174:177], v[114:117]
	v_mfma_f32_16x16x32_bf16 v[110:113], v[150:153], v[182:185], v[110:113]
	v_mfma_f32_16x16x32_bf16 v[106:109], v[158:161], v[182:185], v[106:109]
	v_mfma_f32_16x16x32_bf16 v[102:105], v[150:153], v[190:193], v[102:105]
	v_mfma_f32_16x16x32_bf16 v[98:101], v[158:161], v[190:193], v[98:101]
	v_mfma_f32_16x16x32_bf16 v[126:129], v[154:157], v[170:173], v[126:129]
	v_mfma_f32_16x16x32_bf16 v[122:125], v[162:165], v[170:173], v[122:125]
	v_mfma_f32_16x16x32_bf16 v[118:121], v[154:157], v[178:181], v[118:121]
	v_mfma_f32_16x16x32_bf16 v[114:117], v[162:165], v[178:181], v[114:117]
	v_mfma_f32_16x16x32_bf16 v[110:113], v[154:157], v[186:189], v[110:113]
	v_mfma_f32_16x16x32_bf16 v[106:109], v[162:165], v[186:189], v[106:109]
	v_mfma_f32_16x16x32_bf16 v[102:105], v[154:157], v[196:199], v[102:105]
	v_mfma_f32_16x16x32_bf16 v[98:101], v[162:165], v[196:199], v[98:101]
	s_barrier
	s_add_i32 s44, 0, 0x1c000
	s_add_i32 s45, s67, s50
	v_add_u32_e32 v0, s44, v131
	v_lshl_add_u64 v[200:201], v[200:201], 0, s[12:13]
	s_mov_b32 m0, s45
	ds_read_b128 v[212:215], v0
	ds_read_b128 v[216:219], v0 offset:1024
	ds_read_b128 v[220:223], v0 offset:2048
	ds_read_b128 v[224:227], v0 offset:3072
	global_load_lds_dwordx4 v[200:201], off
	v_lshl_add_u64 v[200:201], v[202:203], 0, s[12:13]
	s_add_i32 m0, s45, 0x2000
	s_nop 0
	global_load_lds_dwordx4 v[200:201], off
	s_barrier
	s_waitcnt lgkmcnt(0)
	s_waitcnt lgkmcnt(0)
	v_mfma_f32_16x16x32_bf16 v[66:69], v[212:215], v[166:169], v[66:69]
	v_mfma_f32_16x16x32_bf16 v[58:61], v[220:223], v[166:169], v[58:61]
	v_mfma_f32_16x16x32_bf16 v[54:57], v[212:215], v[174:177], v[54:57]
	v_mfma_f32_16x16x32_bf16 v[50:53], v[220:223], v[174:177], v[50:53]
	v_mfma_f32_16x16x32_bf16 v[46:49], v[212:215], v[182:185], v[46:49]
	v_mfma_f32_16x16x32_bf16 v[42:45], v[220:223], v[182:185], v[42:45]
	v_mfma_f32_16x16x32_bf16 v[38:41], v[212:215], v[190:193], v[38:41]
	v_mfma_f32_16x16x32_bf16 v[34:37], v[220:223], v[190:193], v[34:37]
	v_mfma_f32_16x16x32_bf16 v[66:69], v[216:219], v[170:173], v[66:69]
	v_mfma_f32_16x16x32_bf16 v[58:61], v[224:227], v[170:173], v[58:61]
	v_mfma_f32_16x16x32_bf16 v[54:57], v[216:219], v[178:181], v[54:57]
	v_mfma_f32_16x16x32_bf16 v[50:53], v[224:227], v[178:181], v[50:53]
	v_mfma_f32_16x16x32_bf16 v[46:49], v[216:219], v[186:189], v[46:49]
	v_mfma_f32_16x16x32_bf16 v[42:45], v[224:227], v[186:189], v[42:45]
	v_mfma_f32_16x16x32_bf16 v[38:41], v[216:219], v[196:199], v[38:41]
	v_mfma_f32_16x16x32_bf16 v[34:37], v[224:227], v[196:199], v[34:37]
	s_mov_b32 m0, s56
	v_lshl_add_u64 v[200:201], v[228:229], 0, s[12:13]
	s_barrier
	ds_read_b128 v[166:169], v139 offset:49152
	ds_read_b128 v[170:173], v139 offset:50176
	ds_read_b128 v[174:177], v139 offset:51200
	ds_read_b128 v[178:181], v139 offset:52224
	ds_read_b128 v[182:185], v139 offset:53248
	ds_read_b128 v[186:189], v139 offset:54272
	ds_read_b128 v[190:193], v139 offset:55296
	ds_read_b128 v[196:199], v139 offset:56320
	global_load_lds_dwordx4 v[200:201], off
	v_lshl_add_u64 v[200:201], v[230:231], 0, s[12:13]
	s_mov_b32 m0, s57
	s_nop 0
	global_load_lds_dwordx4 v[200:201], off
	s_barrier
	s_waitcnt lgkmcnt(0)
	s_waitcnt lgkmcnt(0)
	v_mfma_f32_16x16x32_bf16 v[94:97], v[150:153], v[166:169], v[94:97]
	v_mfma_f32_16x16x32_bf16 v[90:93], v[158:161], v[166:169], v[90:93]
	v_mfma_f32_16x16x32_bf16 v[86:89], v[150:153], v[174:177], v[86:89]
	v_mfma_f32_16x16x32_bf16 v[82:85], v[158:161], v[174:177], v[82:85]
	v_mfma_f32_16x16x32_bf16 v[78:81], v[150:153], v[182:185], v[78:81]
	v_mfma_f32_16x16x32_bf16 v[74:77], v[158:161], v[182:185], v[74:77]
	v_mfma_f32_16x16x32_bf16 v[70:73], v[150:153], v[190:193], v[70:73]
	v_mfma_f32_16x16x32_bf16 v[62:65], v[158:161], v[190:193], v[62:65]
	v_mfma_f32_16x16x32_bf16 v[94:97], v[154:157], v[170:173], v[94:97]
	v_mfma_f32_16x16x32_bf16 v[90:93], v[162:165], v[170:173], v[90:93]
	v_mfma_f32_16x16x32_bf16 v[86:89], v[154:157], v[178:181], v[86:89]
	v_mfma_f32_16x16x32_bf16 v[82:85], v[162:165], v[178:181], v[82:85]
	v_mfma_f32_16x16x32_bf16 v[78:81], v[154:157], v[186:189], v[78:81]
	v_mfma_f32_16x16x32_bf16 v[74:77], v[162:165], v[186:189], v[74:77]
	v_mfma_f32_16x16x32_bf16 v[70:73], v[154:157], v[196:199], v[70:73]
	v_mfma_f32_16x16x32_bf16 v[62:65], v[162:165], v[196:199], v[62:65]
	s_barrier
	s_add_u32 s42, s42, 0x40080
	s_addc_u32 s43, s43, 0
	s_add_i32 s44, s44, s50
	v_lshl_add_u64 v[150:151], s[42:43], 0, v[206:207]
	s_mov_b32 m0, s44
	s_nop 0
	global_load_lds_dwordx4 v[150:151], off
	v_lshl_add_u64 v[150:151], s[42:43], 0, v[210:211]
	s_add_i32 m0, s44, 0x2000
	s_nop 0
	global_load_lds_dwordx4 v[150:151], off
	s_waitcnt vmcnt(6)
	s_barrier
	v_mfma_f32_16x16x32_bf16 v[30:33], v[212:215], v[166:169], v[30:33]
	v_mfma_f32_16x16x32_bf16 v[26:29], v[220:223], v[166:169], v[26:29]
	v_mfma_f32_16x16x32_bf16 v[22:25], v[212:215], v[174:177], v[22:25]
	v_mfma_f32_16x16x32_bf16 v[18:21], v[220:223], v[174:177], v[18:21]
	v_mfma_f32_16x16x32_bf16 v[14:17], v[212:215], v[182:185], v[14:17]
	v_mfma_f32_16x16x32_bf16 v[10:13], v[220:223], v[182:185], v[10:13]
	v_mfma_f32_16x16x32_bf16 v[6:9], v[212:215], v[190:193], v[6:9]
	v_mfma_f32_16x16x32_bf16 v[2:5], v[220:223], v[190:193], v[2:5]
	v_mfma_f32_16x16x32_bf16 v[30:33], v[216:219], v[170:173], v[30:33]
	v_mfma_f32_16x16x32_bf16 v[26:29], v[224:227], v[170:173], v[26:29]
	v_mfma_f32_16x16x32_bf16 v[22:25], v[216:219], v[178:181], v[22:25]
	v_mfma_f32_16x16x32_bf16 v[18:21], v[224:227], v[178:181], v[18:21]
	v_mfma_f32_16x16x32_bf16 v[14:17], v[216:219], v[186:189], v[14:17]
	v_mfma_f32_16x16x32_bf16 v[10:13], v[224:227], v[186:189], v[10:13]
	v_mfma_f32_16x16x32_bf16 v[6:9], v[216:219], v[196:199], v[6:9]
	v_mfma_f32_16x16x32_bf16 v[2:5], v[224:227], v[196:199], v[2:5]
	s_add_i32 s66, s66, 2
	s_add_u32 s29, s29, 0x100
	s_addc_u32 s59, s59, 0
	s_add_u32 s40, s40, 0x100
	s_addc_u32 s41, s41, 0
	s_cmp_gt_u32 s66, 13
	s_barrier
	s_cbranch_scc0 .LBB0_1786
	s_ashr_i32 s40, s26, 1
	s_ashr_i32 s41, s40, 31
	s_lshl_b32 s5, s28, 8
	s_lshl_b64 s[40:41], s[40:41], 20
	s_add_i32 s5, s5, s55
	s_bitcmp1_b32 s26, 0
	s_cselect_b64 s[26:27], -1, 0
	s_ashr_i32 s9, s5, 6
	s_and_b32 s9, s9, -4
	s_or_b32 s28, s9, s61
	s_ashr_i32 s29, s28, 31
	v_lshl_add_u64 v[152:153], v[142:143], 0, s[40:41]
	s_lshl_b64 s[42:43], s[28:29], 15
	v_lshl_add_u64 v[156:157], v[152:153], 0, s[42:43]
	s_mov_b64 s[42:43], -1
	s_and_b64 vcc, exec, s[26:27]
	v_lshlrev_b32_e32 v150, 1, v194
	s_cbranch_vccz .LBB0_1789
	s_lshl_b32 s10, s62, 1
	v_lshl_add_u64 v[154:155], v[156:157], 0, s[10:11]
	v_mov_b32_e32 v151, v1
	v_lshl_add_u64 v[154:155], v[154:155], 0, v[150:151]
	v_cvt_pk_bf16_f32 v0, v126, s0
	global_store_short v[154:155], v0, off
	v_cvt_pk_bf16_f32 v0, v122, s0
	global_store_short v[154:155], v0, off offset:256
	v_cvt_pk_bf16_f32 v0, v127, s0
	global_store_short v[154:155], v0, off offset:64
	v_cvt_pk_bf16_f32 v0, v123, s0
	global_store_short v[154:155], v0, off offset:320
	v_cvt_pk_bf16_f32 v0, v128, s0
	global_store_short v[154:155], v0, off offset:128
	v_cvt_pk_bf16_f32 v0, v124, s0
	global_store_short v[154:155], v0, off offset:384
	v_cvt_pk_bf16_f32 v0, v129, s0
	global_store_short v[154:155], v0, off offset:192
	v_cvt_pk_bf16_f32 v0, v125, s0
	global_store_short v[154:155], v0, off offset:448
	s_mov_b64 s[42:43], 0
